# P0 adaLN gemv hand-written: 32 weight rows in flight per wave, accumulators transposed through per-wave LDS so each f32 atomic instruction covers 256 contiguous bytes
# speedup vs baseline: 1.0097x; 1.0097x over previous
; __device__ __forceinline__ float silu_f(float v) { return v * __builtin_amdgcn_rcpf(1.f + __builtin_amdgcn_exp2f(-1.4426950408889634f * v)); }
; __device__ __forceinline__ void gemv_item(const float* c, const float* c_ctx, const float* ada_w, const float* ada_b, float* mod, int it, int lane) {
;     const int l = it / 768, rem = it % 768, kc = rem / 24, cgp = rem % 24, k0 = kc * 64;
;     float s[9];
; #pragma unroll
;     for (int r = 0; r < 8; ++r) s[r] = silu_f(c[r * DM + k0 + lane]);
;     s[8] = silu_f(c_ctx[k0 + lane]);
;     const float* W = ada_w + (size_t)l * DM * 6144 + (size_t)k0 * 6144 + cgp * 256 + lane * 4;
;     f32x4 acc[9];
; #pragma unroll
;     for (int r = 0; r < 9; ++r) acc[r] = (f32x4){0.f, 0.f, 0.f, 0.f};
; #pragma unroll 16
;     for (int kk = 0; kk < 64; ++kk) { const f32x4 w = *(const f32x4*)(W + (size_t)kk * 6144);
; #pragma unroll
;         for (int r = 0; r < 9; ++r) { const float sk = __uint_as_float(__builtin_amdgcn_readlane(__float_as_uint(s[r]), kk)); acc[r] += w * sk; } }
;     const int col = cgp * 256 + lane * 4;
;     f32x4 bv = (f32x4){0.f, 0.f, 0.f, 0.f};
;     if (kc == 0) bv = *(const f32x4*)(ada_b + l * 6144 + col);
.LBB0_92:
	s_and_b64 vcc, exec, s[0:1]
	s_cbranch_vccz .LBB0_124
	s_cmpk_lt_u32 s57, 0xc0
	s_cselect_b64 s[8:9], -1, 0
	s_cmpk_gt_u32 s57, 0xbf
	s_mov_b32 s0, 4
	s_cbranch_scc1 .LBB0_102
	s_mul_i32 s0, s2, 3
	s_add_i32 s0, s0, s3
	s_mul_i32 s1, s0, 2731
	s_lshr_b32 s1, s1, 16
	s_mul_i32 s4, s1, 24
	s_sub_i32 s4, s0, s4
	v_lshlrev_b32_e32 v45, 2, v77
	v_lshlrev_b32_e32 v46, 4, v77
	s_lshl_b32 s5, s1, 8
	s_add_u32 s20, s70, s5
	s_addc_u32 s21, s71, 0
	global_load_dword v36, v45, s[20:21]
	s_add_u32 s20, s20, 0x2000
	s_addc_u32 s21, s21, 0
	global_load_dword v37, v45, s[20:21]
	s_add_u32 s20, s20, 0x2000
	s_addc_u32 s21, s21, 0
	global_load_dword v38, v45, s[20:21]
	s_add_u32 s20, s20, 0x2000
	s_addc_u32 s21, s21, 0
	global_load_dword v39, v45, s[20:21]
	s_add_u32 s20, s20, 0x2000
	s_addc_u32 s21, s21, 0
	global_load_dword v40, v45, s[20:21]
	s_add_u32 s20, s20, 0x2000
	s_addc_u32 s21, s21, 0
	global_load_dword v41, v45, s[20:21]
	s_add_u32 s20, s20, 0x2000
	s_addc_u32 s21, s21, 0
	global_load_dword v42, v45, s[20:21]
	s_add_u32 s20, s20, 0x2000
	s_addc_u32 s21, s21, 0
	global_load_dword v43, v45, s[20:21]
	s_add_u32 s20, s74, s5
	s_addc_u32 s21, s75, 0
	global_load_dword v44, v45, s[20:21]
	s_mul_i32 s5, s1, 0x180000
	s_lshl_b32 s6, s4, 10
	s_add_i32 s5, s5, s6
	s_add_u32 s22, s76, s5
	s_addc_u32 s23, s77, 0
	global_load_dwordx4 v[80:83], v46, s[22:23]
	s_add_u32 s22, s22, 0x6000
	s_addc_u32 s23, s23, 0
	global_load_dwordx4 v[84:87], v46, s[22:23]
	s_add_u32 s22, s22, 0x6000
	s_addc_u32 s23, s23, 0
	global_load_dwordx4 v[88:91], v46, s[22:23]
	s_add_u32 s22, s22, 0x6000
	s_addc_u32 s23, s23, 0
	global_load_dwordx4 v[92:95], v46, s[22:23]
	s_add_u32 s22, s22, 0x6000
	s_addc_u32 s23, s23, 0
	global_load_dwordx4 v[96:99], v46, s[22:23]
	s_add_u32 s22, s22, 0x6000
	s_addc_u32 s23, s23, 0
	global_load_dwordx4 v[100:103], v46, s[22:23]
	s_add_u32 s22, s22, 0x6000
	s_addc_u32 s23, s23, 0
	global_load_dwordx4 v[104:107], v46, s[22:23]
	s_add_u32 s22, s22, 0x6000
	s_addc_u32 s23, s23, 0
	global_load_dwordx4 v[108:111], v46, s[22:23]
	s_add_u32 s22, s22, 0x6000
	s_addc_u32 s23, s23, 0
	global_load_dwordx4 v[112:115], v46, s[22:23]
	s_add_u32 s22, s22, 0x6000
	s_addc_u32 s23, s23, 0
	global_load_dwordx4 v[116:119], v46, s[22:23]
	s_add_u32 s22, s22, 0x6000
	s_addc_u32 s23, s23, 0
	global_load_dwordx4 v[120:123], v46, s[22:23]
	s_add_u32 s22, s22, 0x6000
	s_addc_u32 s23, s23, 0
	global_load_dwordx4 v[124:127], v46, s[22:23]
	s_add_u32 s22, s22, 0x6000
	s_addc_u32 s23, s23, 0
	global_load_dwordx4 v[128:131], v46, s[22:23]
	s_add_u32 s22, s22, 0x6000
	s_addc_u32 s23, s23, 0
	global_load_dwordx4 v[132:135], v46, s[22:23]
	s_add_u32 s22, s22, 0x6000
	s_addc_u32 s23, s23, 0
	global_load_dwordx4 v[136:139], v46, s[22:23]
	s_add_u32 s22, s22, 0x6000
	s_addc_u32 s23, s23, 0
	global_load_dwordx4 v[140:143], v46, s[22:23]
	s_add_u32 s22, s22, 0x6000
	s_addc_u32 s23, s23, 0
	global_load_dwordx4 v[144:147], v46, s[22:23]
	s_add_u32 s22, s22, 0x6000
	s_addc_u32 s23, s23, 0
	global_load_dwordx4 v[148:151], v46, s[22:23]
	s_add_u32 s22, s22, 0x6000
	s_addc_u32 s23, s23, 0
	global_load_dwordx4 v[152:155], v46, s[22:23]
	s_add_u32 s22, s22, 0x6000
	s_addc_u32 s23, s23, 0
	global_load_dwordx4 v[156:159], v46, s[22:23]
	s_add_u32 s22, s22, 0x6000
	s_addc_u32 s23, s23, 0
	global_load_dwordx4 v[160:163], v46, s[22:23]
	s_add_u32 s22, s22, 0x6000
	s_addc_u32 s23, s23, 0
	global_load_dwordx4 v[164:167], v46, s[22:23]
	s_add_u32 s22, s22, 0x6000
	s_addc_u32 s23, s23, 0
	global_load_dwordx4 v[168:171], v46, s[22:23]
	s_add_u32 s22, s22, 0x6000
	s_addc_u32 s23, s23, 0
	global_load_dwordx4 v[172:175], v46, s[22:23]
	s_add_u32 s22, s22, 0x6000
	s_addc_u32 s23, s23, 0
	global_load_dwordx4 v[176:179], v46, s[22:23]
	s_add_u32 s22, s22, 0x6000
	s_addc_u32 s23, s23, 0
	global_load_dwordx4 v[180:183], v46, s[22:23]
	s_add_u32 s22, s22, 0x6000
	s_addc_u32 s23, s23, 0
	global_load_dwordx4 v[184:187], v46, s[22:23]
	s_add_u32 s22, s22, 0x6000
	s_addc_u32 s23, s23, 0
	global_load_dwordx4 v[188:191], v46, s[22:23]
	s_add_u32 s22, s22, 0x6000
	s_addc_u32 s23, s23, 0
	global_load_dwordx4 v[192:195], v46, s[22:23]
	s_add_u32 s22, s22, 0x6000
	s_addc_u32 s23, s23, 0
	global_load_dwordx4 v[200:203], v46, s[22:23]
	s_add_u32 s22, s22, 0x6000
	s_addc_u32 s23, s23, 0
	global_load_dwordx4 v[204:207], v46, s[22:23]
	s_add_u32 s22, s22, 0x6000
	s_addc_u32 s23, s23, 0
	global_load_dwordx4 v[208:211], v46, s[22:23]
	s_add_u32 s22, s22, 0x6000
	s_addc_u32 s23, s23, 0
	v_mov_b32_e32 v52, 0
	v_mov_b32_e32 v53, 0
	v_mov_b32_e32 v54, 0
	v_mov_b32_e32 v55, 0
	s_cmp_lg_u32 s1, 0
	s_cbranch_scc1 .Lgv0_nobias
	s_lshl_b32 s5, s4, 10
	s_add_u32 s20, s78, s5
	s_addc_u32 s21, s79, 0
	global_load_dwordx4 v[52:55], v46, s[20:21]
	s_waitcnt vmcnt(0)
; __device__ __forceinline__ float silu_f(float v) { return v * __builtin_amdgcn_rcpf(1.f + __builtin_amdgcn_exp2f(-1.4426950408889634f * v)); }
; __device__ __forceinline__ void gemv_item(const float* c, const float* c_ctx, const float* ada_w, const float* ada_b, float* mod, int it, int lane) {
;     ...
;     for (int r = 0; r < 8; ++r) s[r] = silu_f(c[r * DM + k0 + lane]);
;     s[8] = silu_f(c_ctx[k0 + lane]);
;     const float* W = ada_w + (size_t)l * DM * 6144 + (size_t)k0 * 6144 + cgp * 256 + lane * 4;
;     f32x4 acc[9];
; #pragma unroll
;     for (int r = 0; r < 9; ++r) acc[r] = (f32x4){0.f, 0.f, 0.f, 0.f};
; #pragma unroll 16
;     for (int kk = 0; kk < 64; ++kk) { const f32x4 w = *(const f32x4*)(W + (size_t)kk * 6144);
; #pragma unroll
;         for (int r = 0; r < 9; ++r) { const float sk = __uint_as_float(__builtin_amdgcn_readlane(__float_as_uint(s[r]), kk)); acc[r] += w * sk; } }
.Lgv0_nobias:
	s_waitcnt vmcnt(32)
	v_mul_f32_e32 v47, 0xbfb8aa3b, v36
	v_exp_f32_e32 v47, v47
	s_nop 0
	v_add_f32_e32 v47, 1.0, v47
	v_rcp_f32_e32 v47, v47
	s_nop 0
	v_mul_f32_e32 v36, v36, v47
	v_mul_f32_e32 v47, 0xbfb8aa3b, v37
	v_exp_f32_e32 v47, v47
	s_nop 0
	v_add_f32_e32 v47, 1.0, v47
	v_rcp_f32_e32 v47, v47
	s_nop 0
	v_mul_f32_e32 v37, v37, v47
	v_mul_f32_e32 v47, 0xbfb8aa3b, v38
	v_exp_f32_e32 v47, v47
	s_nop 0
	v_add_f32_e32 v47, 1.0, v47
	v_rcp_f32_e32 v47, v47
	s_nop 0
	v_mul_f32_e32 v38, v38, v47
	v_mul_f32_e32 v47, 0xbfb8aa3b, v39
	v_exp_f32_e32 v47, v47
	s_nop 0
	v_add_f32_e32 v47, 1.0, v47
	v_rcp_f32_e32 v47, v47
	s_nop 0
	v_mul_f32_e32 v39, v39, v47
	v_mul_f32_e32 v47, 0xbfb8aa3b, v40
	v_exp_f32_e32 v47, v47
	s_nop 0
	v_add_f32_e32 v47, 1.0, v47
	v_rcp_f32_e32 v47, v47
	s_nop 0
	v_mul_f32_e32 v40, v40, v47
	v_mul_f32_e32 v47, 0xbfb8aa3b, v41
	v_exp_f32_e32 v47, v47
	s_nop 0
	v_add_f32_e32 v47, 1.0, v47
	v_rcp_f32_e32 v47, v47
	s_nop 0
	v_mul_f32_e32 v41, v41, v47
	v_mul_f32_e32 v47, 0xbfb8aa3b, v42
	v_exp_f32_e32 v47, v47
	s_nop 0
	v_add_f32_e32 v47, 1.0, v47
	v_rcp_f32_e32 v47, v47
	s_nop 0
	v_mul_f32_e32 v42, v42, v47
	v_mul_f32_e32 v47, 0xbfb8aa3b, v43
	v_exp_f32_e32 v47, v47
	s_nop 0
	v_add_f32_e32 v47, 1.0, v47
	v_rcp_f32_e32 v47, v47
	s_nop 0
	v_mul_f32_e32 v43, v43, v47
	v_mul_f32_e32 v47, 0xbfb8aa3b, v44
	v_exp_f32_e32 v47, v47
	s_nop 0
	v_add_f32_e32 v47, 1.0, v47
	v_rcp_f32_e32 v47, v47
	s_nop 0
	v_mul_f32_e32 v44, v44, v47
	v_mov_b32_e32 v0, 0
	v_mov_b32_e32 v1, 0
	v_mov_b32_e32 v2, 0
	v_mov_b32_e32 v3, 0
	v_mov_b32_e32 v4, 0
	v_mov_b32_e32 v5, 0
	v_mov_b32_e32 v6, 0
	v_mov_b32_e32 v7, 0
	v_mov_b32_e32 v8, 0
	v_mov_b32_e32 v9, 0
	v_mov_b32_e32 v10, 0
	v_mov_b32_e32 v11, 0
	v_mov_b32_e32 v12, 0
	v_mov_b32_e32 v13, 0
	v_mov_b32_e32 v14, 0
	v_mov_b32_e32 v15, 0
	v_mov_b32_e32 v16, 0
	v_mov_b32_e32 v17, 0
	v_mov_b32_e32 v18, 0
	v_mov_b32_e32 v19, 0
	v_mov_b32_e32 v20, 0
	v_mov_b32_e32 v21, 0
	v_mov_b32_e32 v22, 0
	v_mov_b32_e32 v23, 0
	v_mov_b32_e32 v24, 0
	v_mov_b32_e32 v25, 0
	v_mov_b32_e32 v26, 0
	v_mov_b32_e32 v27, 0
	v_mov_b32_e32 v28, 0
	v_mov_b32_e32 v29, 0
	v_mov_b32_e32 v30, 0
	v_mov_b32_e32 v31, 0
	v_mov_b32_e32 v32, 0
	v_mov_b32_e32 v33, 0
	v_mov_b32_e32 v34, 0
	v_mov_b32_e32 v35, 0
	s_waitcnt vmcnt(16)
	v_readlane_b32 s10, v36, 0
	v_readlane_b32 s11, v37, 0
	v_readlane_b32 s12, v38, 0
	v_readlane_b32 s13, v39, 0
	v_readlane_b32 s14, v40, 0
	v_readlane_b32 s15, v41, 0
	v_readlane_b32 s16, v42, 0
	v_readlane_b32 s17, v43, 0
	v_readlane_b32 s18, v44, 0
	v_fmac_f32_e32 v0, s10, v80
	v_fmac_f32_e32 v1, s10, v81
	v_fmac_f32_e32 v2, s10, v82
	v_fmac_f32_e32 v3, s10, v83
	v_fmac_f32_e32 v4, s11, v80
	v_fmac_f32_e32 v5, s11, v81
	v_fmac_f32_e32 v6, s11, v82
	v_fmac_f32_e32 v7, s11, v83
	v_fmac_f32_e32 v8, s12, v80
	v_fmac_f32_e32 v9, s12, v81
	v_fmac_f32_e32 v10, s12, v82
	v_fmac_f32_e32 v11, s12, v83
	v_fmac_f32_e32 v12, s13, v80
	v_fmac_f32_e32 v13, s13, v81
	v_fmac_f32_e32 v14, s13, v82
	v_fmac_f32_e32 v15, s13, v83
	v_fmac_f32_e32 v16, s14, v80
	v_fmac_f32_e32 v17, s14, v81
	v_fmac_f32_e32 v18, s14, v82
	v_fmac_f32_e32 v19, s14, v83
	v_fmac_f32_e32 v20, s15, v80
	v_fmac_f32_e32 v21, s15, v81
	v_fmac_f32_e32 v22, s15, v82
	v_fmac_f32_e32 v23, s15, v83
	v_fmac_f32_e32 v24, s16, v80
	v_fmac_f32_e32 v25, s16, v81
	v_fmac_f32_e32 v26, s16, v82
	v_fmac_f32_e32 v27, s16, v83
	v_fmac_f32_e32 v28, s17, v80
	v_fmac_f32_e32 v29, s17, v81
	v_fmac_f32_e32 v30, s17, v82
	v_fmac_f32_e32 v31, s17, v83
	v_fmac_f32_e32 v32, s18, v80
	v_fmac_f32_e32 v33, s18, v81
	v_fmac_f32_e32 v34, s18, v82
	v_fmac_f32_e32 v35, s18, v83
	v_readlane_b32 s10, v36, 1
	v_readlane_b32 s11, v37, 1
	v_readlane_b32 s12, v38, 1
	v_readlane_b32 s13, v39, 1
	v_readlane_b32 s14, v40, 1
	v_readlane_b32 s15, v41, 1
	v_readlane_b32 s16, v42, 1
	v_readlane_b32 s17, v43, 1
	v_readlane_b32 s18, v44, 1
	v_fmac_f32_e32 v0, s10, v84
	v_fmac_f32_e32 v1, s10, v85
	v_fmac_f32_e32 v2, s10, v86
	v_fmac_f32_e32 v3, s10, v87
	v_fmac_f32_e32 v4, s11, v84
	v_fmac_f32_e32 v5, s11, v85
	v_fmac_f32_e32 v6, s11, v86
	v_fmac_f32_e32 v7, s11, v87
	v_fmac_f32_e32 v8, s12, v84
	v_fmac_f32_e32 v9, s12, v85
	v_fmac_f32_e32 v10, s12, v86
	v_fmac_f32_e32 v11, s12, v87
	v_fmac_f32_e32 v12, s13, v84
	v_fmac_f32_e32 v13, s13, v85
	v_fmac_f32_e32 v14, s13, v86
	v_fmac_f32_e32 v15, s13, v87
	v_fmac_f32_e32 v16, s14, v84
	v_fmac_f32_e32 v17, s14, v85
	v_fmac_f32_e32 v18, s14, v86
	v_fmac_f32_e32 v19, s14, v87
	v_fmac_f32_e32 v20, s15, v84
	v_fmac_f32_e32 v21, s15, v85
	v_fmac_f32_e32 v22, s15, v86
	v_fmac_f32_e32 v23, s15, v87
	v_fmac_f32_e32 v24, s16, v84
	v_fmac_f32_e32 v25, s16, v85
	v_fmac_f32_e32 v26, s16, v86
	v_fmac_f32_e32 v27, s16, v87
	v_fmac_f32_e32 v28, s17, v84
	v_fmac_f32_e32 v29, s17, v85
	v_fmac_f32_e32 v30, s17, v86
	v_fmac_f32_e32 v31, s17, v87
	v_fmac_f32_e32 v32, s18, v84
	v_fmac_f32_e32 v33, s18, v85
	v_fmac_f32_e32 v34, s18, v86
	v_fmac_f32_e32 v35, s18, v87
	v_readlane_b32 s10, v36, 2
	v_readlane_b32 s11, v37, 2
	v_readlane_b32 s12, v38, 2
	v_readlane_b32 s13, v39, 2
	v_readlane_b32 s14, v40, 2
	v_readlane_b32 s15, v41, 2
	v_readlane_b32 s16, v42, 2
	v_readlane_b32 s17, v43, 2
	v_readlane_b32 s18, v44, 2
	v_fmac_f32_e32 v0, s10, v88
	v_fmac_f32_e32 v1, s10, v89
	v_fmac_f32_e32 v2, s10, v90
	v_fmac_f32_e32 v3, s10, v91
	v_fmac_f32_e32 v4, s11, v88
	v_fmac_f32_e32 v5, s11, v89
	v_fmac_f32_e32 v6, s11, v90
	v_fmac_f32_e32 v7, s11, v91
	v_fmac_f32_e32 v8, s12, v88
	v_fmac_f32_e32 v9, s12, v89
	v_fmac_f32_e32 v10, s12, v90
	v_fmac_f32_e32 v11, s12, v91
	v_fmac_f32_e32 v12, s13, v88
	v_fmac_f32_e32 v13, s13, v89
	v_fmac_f32_e32 v14, s13, v90
	v_fmac_f32_e32 v15, s13, v91
; __device__ __forceinline__ void gemv_item(const float* c, const float* c_ctx, const float* ada_w, const float* ada_b, float* mod, int it, int lane) {
;     ...
;     for (int kk = 0; kk < 64; ++kk) { const f32x4 w = *(const f32x4*)(W + (size_t)kk * 6144);
; #pragma unroll
;         for (int r = 0; r < 9; ++r) { const float sk = __uint_as_float(__builtin_amdgcn_readlane(__float_as_uint(s[r]), kk)); acc[r] += w * sk; } }
	v_fmac_f32_e32 v16, s14, v88
	v_fmac_f32_e32 v17, s14, v89
	v_fmac_f32_e32 v18, s14, v90
	v_fmac_f32_e32 v19, s14, v91
	v_fmac_f32_e32 v20, s15, v88
	v_fmac_f32_e32 v21, s15, v89
	v_fmac_f32_e32 v22, s15, v90
	v_fmac_f32_e32 v23, s15, v91
	v_fmac_f32_e32 v24, s16, v88
	v_fmac_f32_e32 v25, s16, v89
	v_fmac_f32_e32 v26, s16, v90
	v_fmac_f32_e32 v27, s16, v91
	v_fmac_f32_e32 v28, s17, v88
	v_fmac_f32_e32 v29, s17, v89
	v_fmac_f32_e32 v30, s17, v90
	v_fmac_f32_e32 v31, s17, v91
	v_fmac_f32_e32 v32, s18, v88
	v_fmac_f32_e32 v33, s18, v89
	v_fmac_f32_e32 v34, s18, v90
	v_fmac_f32_e32 v35, s18, v91
	v_readlane_b32 s10, v36, 3
	v_readlane_b32 s11, v37, 3
	v_readlane_b32 s12, v38, 3
	v_readlane_b32 s13, v39, 3
	v_readlane_b32 s14, v40, 3
	v_readlane_b32 s15, v41, 3
	v_readlane_b32 s16, v42, 3
	v_readlane_b32 s17, v43, 3
	v_readlane_b32 s18, v44, 3
	v_fmac_f32_e32 v0, s10, v92
	v_fmac_f32_e32 v1, s10, v93
	v_fmac_f32_e32 v2, s10, v94
	v_fmac_f32_e32 v3, s10, v95
	v_fmac_f32_e32 v4, s11, v92
	v_fmac_f32_e32 v5, s11, v93
	v_fmac_f32_e32 v6, s11, v94
	v_fmac_f32_e32 v7, s11, v95
	v_fmac_f32_e32 v8, s12, v92
	v_fmac_f32_e32 v9, s12, v93
	v_fmac_f32_e32 v10, s12, v94
	v_fmac_f32_e32 v11, s12, v95
	v_fmac_f32_e32 v12, s13, v92
	v_fmac_f32_e32 v13, s13, v93
	v_fmac_f32_e32 v14, s13, v94
	v_fmac_f32_e32 v15, s13, v95
	v_fmac_f32_e32 v16, s14, v92
	v_fmac_f32_e32 v17, s14, v93
	v_fmac_f32_e32 v18, s14, v94
	v_fmac_f32_e32 v19, s14, v95
	v_fmac_f32_e32 v20, s15, v92
	v_fmac_f32_e32 v21, s15, v93
	v_fmac_f32_e32 v22, s15, v94
	v_fmac_f32_e32 v23, s15, v95
	v_fmac_f32_e32 v24, s16, v92
	v_fmac_f32_e32 v25, s16, v93
	v_fmac_f32_e32 v26, s16, v94
	v_fmac_f32_e32 v27, s16, v95
	v_fmac_f32_e32 v28, s17, v92
	v_fmac_f32_e32 v29, s17, v93
	v_fmac_f32_e32 v30, s17, v94
	v_fmac_f32_e32 v31, s17, v95
	v_fmac_f32_e32 v32, s18, v92
	v_fmac_f32_e32 v33, s18, v93
	v_fmac_f32_e32 v34, s18, v94
	v_fmac_f32_e32 v35, s18, v95
	v_readlane_b32 s10, v36, 4
	v_readlane_b32 s11, v37, 4
	v_readlane_b32 s12, v38, 4
	v_readlane_b32 s13, v39, 4
	v_readlane_b32 s14, v40, 4
	v_readlane_b32 s15, v41, 4
	v_readlane_b32 s16, v42, 4
	v_readlane_b32 s17, v43, 4
	v_readlane_b32 s18, v44, 4
	v_fmac_f32_e32 v0, s10, v96
	v_fmac_f32_e32 v1, s10, v97
	v_fmac_f32_e32 v2, s10, v98
	v_fmac_f32_e32 v3, s10, v99
	v_fmac_f32_e32 v4, s11, v96
	v_fmac_f32_e32 v5, s11, v97
	v_fmac_f32_e32 v6, s11, v98
	v_fmac_f32_e32 v7, s11, v99
	v_fmac_f32_e32 v8, s12, v96
	v_fmac_f32_e32 v9, s12, v97
	v_fmac_f32_e32 v10, s12, v98
	v_fmac_f32_e32 v11, s12, v99
	v_fmac_f32_e32 v12, s13, v96
	v_fmac_f32_e32 v13, s13, v97
	v_fmac_f32_e32 v14, s13, v98
	v_fmac_f32_e32 v15, s13, v99
	v_fmac_f32_e32 v16, s14, v96
	v_fmac_f32_e32 v17, s14, v97
	v_fmac_f32_e32 v18, s14, v98
	v_fmac_f32_e32 v19, s14, v99
	v_fmac_f32_e32 v20, s15, v96
	v_fmac_f32_e32 v21, s15, v97
	v_fmac_f32_e32 v22, s15, v98
	v_fmac_f32_e32 v23, s15, v99
	v_fmac_f32_e32 v24, s16, v96
	v_fmac_f32_e32 v25, s16, v97
	v_fmac_f32_e32 v26, s16, v98
	v_fmac_f32_e32 v27, s16, v99
	v_fmac_f32_e32 v28, s17, v96
	v_fmac_f32_e32 v29, s17, v97
	v_fmac_f32_e32 v30, s17, v98
	v_fmac_f32_e32 v31, s17, v99
	v_fmac_f32_e32 v32, s18, v96
	v_fmac_f32_e32 v33, s18, v97
	v_fmac_f32_e32 v34, s18, v98
	v_fmac_f32_e32 v35, s18, v99
	v_readlane_b32 s10, v36, 5
	v_readlane_b32 s11, v37, 5
	v_readlane_b32 s12, v38, 5
	v_readlane_b32 s13, v39, 5
	v_readlane_b32 s14, v40, 5
	v_readlane_b32 s15, v41, 5
	v_readlane_b32 s16, v42, 5
	v_readlane_b32 s17, v43, 5
	v_readlane_b32 s18, v44, 5
	v_fmac_f32_e32 v0, s10, v100
	v_fmac_f32_e32 v1, s10, v101
	v_fmac_f32_e32 v2, s10, v102
	v_fmac_f32_e32 v3, s10, v103
	v_fmac_f32_e32 v4, s11, v100
	v_fmac_f32_e32 v5, s11, v101
	v_fmac_f32_e32 v6, s11, v102
	v_fmac_f32_e32 v7, s11, v103
	v_fmac_f32_e32 v8, s12, v100
	v_fmac_f32_e32 v9, s12, v101
	v_fmac_f32_e32 v10, s12, v102
	v_fmac_f32_e32 v11, s12, v103
	v_fmac_f32_e32 v12, s13, v100
	v_fmac_f32_e32 v13, s13, v101
	v_fmac_f32_e32 v14, s13, v102
	v_fmac_f32_e32 v15, s13, v103
	v_fmac_f32_e32 v16, s14, v100
	v_fmac_f32_e32 v17, s14, v101
	v_fmac_f32_e32 v18, s14, v102
	v_fmac_f32_e32 v19, s14, v103
	v_fmac_f32_e32 v20, s15, v100
	v_fmac_f32_e32 v21, s15, v101
	v_fmac_f32_e32 v22, s15, v102
	v_fmac_f32_e32 v23, s15, v103
	v_fmac_f32_e32 v24, s16, v100
	v_fmac_f32_e32 v25, s16, v101
	v_fmac_f32_e32 v26, s16, v102
	v_fmac_f32_e32 v27, s16, v103
	v_fmac_f32_e32 v28, s17, v100
	v_fmac_f32_e32 v29, s17, v101
	v_fmac_f32_e32 v30, s17, v102
	v_fmac_f32_e32 v31, s17, v103
	v_fmac_f32_e32 v32, s18, v100
	v_fmac_f32_e32 v33, s18, v101
	v_fmac_f32_e32 v34, s18, v102
	v_fmac_f32_e32 v35, s18, v103
	v_readlane_b32 s10, v36, 6
	v_readlane_b32 s11, v37, 6
	v_readlane_b32 s12, v38, 6
	v_readlane_b32 s13, v39, 6
	v_readlane_b32 s14, v40, 6
	v_readlane_b32 s15, v41, 6
	v_readlane_b32 s16, v42, 6
	v_readlane_b32 s17, v43, 6
	v_readlane_b32 s18, v44, 6
	v_fmac_f32_e32 v0, s10, v104
	v_fmac_f32_e32 v1, s10, v105
	v_fmac_f32_e32 v2, s10, v106
	v_fmac_f32_e32 v3, s10, v107
	v_fmac_f32_e32 v4, s11, v104
	v_fmac_f32_e32 v5, s11, v105
	v_fmac_f32_e32 v6, s11, v106
	v_fmac_f32_e32 v7, s11, v107
	v_fmac_f32_e32 v8, s12, v104
	v_fmac_f32_e32 v9, s12, v105
	v_fmac_f32_e32 v10, s12, v106
	v_fmac_f32_e32 v11, s12, v107
	v_fmac_f32_e32 v12, s13, v104
	v_fmac_f32_e32 v13, s13, v105
	v_fmac_f32_e32 v14, s13, v106
	v_fmac_f32_e32 v15, s13, v107
	v_fmac_f32_e32 v16, s14, v104
	v_fmac_f32_e32 v17, s14, v105
	v_fmac_f32_e32 v18, s14, v106
	v_fmac_f32_e32 v19, s14, v107
	v_fmac_f32_e32 v20, s15, v104
	v_fmac_f32_e32 v21, s15, v105
	v_fmac_f32_e32 v22, s15, v106
	v_fmac_f32_e32 v23, s15, v107
	v_fmac_f32_e32 v24, s16, v104
	v_fmac_f32_e32 v25, s16, v105
; __device__ __forceinline__ void gemv_item(const float* c, const float* c_ctx, const float* ada_w, const float* ada_b, float* mod, int it, int lane) {
;     ...
;     for (int kk = 0; kk < 64; ++kk) { const f32x4 w = *(const f32x4*)(W + (size_t)kk * 6144);
; #pragma unroll
;         for (int r = 0; r < 9; ++r) { const float sk = __uint_as_float(__builtin_amdgcn_readlane(__float_as_uint(s[r]), kk)); acc[r] += w * sk; } }
	v_fmac_f32_e32 v26, s16, v106
	v_fmac_f32_e32 v27, s16, v107
	v_fmac_f32_e32 v28, s17, v104
	v_fmac_f32_e32 v29, s17, v105
	v_fmac_f32_e32 v30, s17, v106
	v_fmac_f32_e32 v31, s17, v107
	v_fmac_f32_e32 v32, s18, v104
	v_fmac_f32_e32 v33, s18, v105
	v_fmac_f32_e32 v34, s18, v106
	v_fmac_f32_e32 v35, s18, v107
	v_readlane_b32 s10, v36, 7
	v_readlane_b32 s11, v37, 7
	v_readlane_b32 s12, v38, 7
	v_readlane_b32 s13, v39, 7
	v_readlane_b32 s14, v40, 7
	v_readlane_b32 s15, v41, 7
	v_readlane_b32 s16, v42, 7
	v_readlane_b32 s17, v43, 7
	v_readlane_b32 s18, v44, 7
	v_fmac_f32_e32 v0, s10, v108
	v_fmac_f32_e32 v1, s10, v109
	v_fmac_f32_e32 v2, s10, v110
	v_fmac_f32_e32 v3, s10, v111
	v_fmac_f32_e32 v4, s11, v108
	v_fmac_f32_e32 v5, s11, v109
	v_fmac_f32_e32 v6, s11, v110
	v_fmac_f32_e32 v7, s11, v111
	v_fmac_f32_e32 v8, s12, v108
	v_fmac_f32_e32 v9, s12, v109
	v_fmac_f32_e32 v10, s12, v110
	v_fmac_f32_e32 v11, s12, v111
	v_fmac_f32_e32 v12, s13, v108
	v_fmac_f32_e32 v13, s13, v109
	v_fmac_f32_e32 v14, s13, v110
	v_fmac_f32_e32 v15, s13, v111
	v_fmac_f32_e32 v16, s14, v108
	v_fmac_f32_e32 v17, s14, v109
	v_fmac_f32_e32 v18, s14, v110
	v_fmac_f32_e32 v19, s14, v111
	v_fmac_f32_e32 v20, s15, v108
	v_fmac_f32_e32 v21, s15, v109
	v_fmac_f32_e32 v22, s15, v110
	v_fmac_f32_e32 v23, s15, v111
	v_fmac_f32_e32 v24, s16, v108
	v_fmac_f32_e32 v25, s16, v109
	v_fmac_f32_e32 v26, s16, v110
	v_fmac_f32_e32 v27, s16, v111
	v_fmac_f32_e32 v28, s17, v108
	v_fmac_f32_e32 v29, s17, v109
	v_fmac_f32_e32 v30, s17, v110
	v_fmac_f32_e32 v31, s17, v111
	v_fmac_f32_e32 v32, s18, v108
	v_fmac_f32_e32 v33, s18, v109
	v_fmac_f32_e32 v34, s18, v110
	v_fmac_f32_e32 v35, s18, v111
	v_readlane_b32 s10, v36, 8
	v_readlane_b32 s11, v37, 8
	v_readlane_b32 s12, v38, 8
	v_readlane_b32 s13, v39, 8
	v_readlane_b32 s14, v40, 8
	v_readlane_b32 s15, v41, 8
	v_readlane_b32 s16, v42, 8
	v_readlane_b32 s17, v43, 8
	v_readlane_b32 s18, v44, 8
	v_fmac_f32_e32 v0, s10, v112
	v_fmac_f32_e32 v1, s10, v113
	v_fmac_f32_e32 v2, s10, v114
	v_fmac_f32_e32 v3, s10, v115
	v_fmac_f32_e32 v4, s11, v112
	v_fmac_f32_e32 v5, s11, v113
	v_fmac_f32_e32 v6, s11, v114
	v_fmac_f32_e32 v7, s11, v115
	v_fmac_f32_e32 v8, s12, v112
	v_fmac_f32_e32 v9, s12, v113
	v_fmac_f32_e32 v10, s12, v114
	v_fmac_f32_e32 v11, s12, v115
	v_fmac_f32_e32 v12, s13, v112
	v_fmac_f32_e32 v13, s13, v113
	v_fmac_f32_e32 v14, s13, v114
	v_fmac_f32_e32 v15, s13, v115
	v_fmac_f32_e32 v16, s14, v112
	v_fmac_f32_e32 v17, s14, v113
	v_fmac_f32_e32 v18, s14, v114
	v_fmac_f32_e32 v19, s14, v115
	v_fmac_f32_e32 v20, s15, v112
	v_fmac_f32_e32 v21, s15, v113
	v_fmac_f32_e32 v22, s15, v114
	v_fmac_f32_e32 v23, s15, v115
	v_fmac_f32_e32 v24, s16, v112
	v_fmac_f32_e32 v25, s16, v113
	v_fmac_f32_e32 v26, s16, v114
	v_fmac_f32_e32 v27, s16, v115
	v_fmac_f32_e32 v28, s17, v112
	v_fmac_f32_e32 v29, s17, v113
	v_fmac_f32_e32 v30, s17, v114
	v_fmac_f32_e32 v31, s17, v115
	v_fmac_f32_e32 v32, s18, v112
	v_fmac_f32_e32 v33, s18, v113
	v_fmac_f32_e32 v34, s18, v114
	v_fmac_f32_e32 v35, s18, v115
	v_readlane_b32 s10, v36, 9
	v_readlane_b32 s11, v37, 9
	v_readlane_b32 s12, v38, 9
	v_readlane_b32 s13, v39, 9
	v_readlane_b32 s14, v40, 9
	v_readlane_b32 s15, v41, 9
	v_readlane_b32 s16, v42, 9
	v_readlane_b32 s17, v43, 9
	v_readlane_b32 s18, v44, 9
	v_fmac_f32_e32 v0, s10, v116
	v_fmac_f32_e32 v1, s10, v117
	v_fmac_f32_e32 v2, s10, v118
	v_fmac_f32_e32 v3, s10, v119
	v_fmac_f32_e32 v4, s11, v116
	v_fmac_f32_e32 v5, s11, v117
	v_fmac_f32_e32 v6, s11, v118
	v_fmac_f32_e32 v7, s11, v119
	v_fmac_f32_e32 v8, s12, v116
	v_fmac_f32_e32 v9, s12, v117
	v_fmac_f32_e32 v10, s12, v118
	v_fmac_f32_e32 v11, s12, v119
	v_fmac_f32_e32 v12, s13, v116
	v_fmac_f32_e32 v13, s13, v117
	v_fmac_f32_e32 v14, s13, v118
	v_fmac_f32_e32 v15, s13, v119
	v_fmac_f32_e32 v16, s14, v116
	v_fmac_f32_e32 v17, s14, v117
	v_fmac_f32_e32 v18, s14, v118
	v_fmac_f32_e32 v19, s14, v119
	v_fmac_f32_e32 v20, s15, v116
	v_fmac_f32_e32 v21, s15, v117
	v_fmac_f32_e32 v22, s15, v118
	v_fmac_f32_e32 v23, s15, v119
	v_fmac_f32_e32 v24, s16, v116
	v_fmac_f32_e32 v25, s16, v117
	v_fmac_f32_e32 v26, s16, v118
	v_fmac_f32_e32 v27, s16, v119
	v_fmac_f32_e32 v28, s17, v116
	v_fmac_f32_e32 v29, s17, v117
	v_fmac_f32_e32 v30, s17, v118
	v_fmac_f32_e32 v31, s17, v119
	v_fmac_f32_e32 v32, s18, v116
	v_fmac_f32_e32 v33, s18, v117
	v_fmac_f32_e32 v34, s18, v118
	v_fmac_f32_e32 v35, s18, v119
	v_readlane_b32 s10, v36, 10
	v_readlane_b32 s11, v37, 10
	v_readlane_b32 s12, v38, 10
	v_readlane_b32 s13, v39, 10
	v_readlane_b32 s14, v40, 10
	v_readlane_b32 s15, v41, 10
	v_readlane_b32 s16, v42, 10
	v_readlane_b32 s17, v43, 10
	v_readlane_b32 s18, v44, 10
	v_fmac_f32_e32 v0, s10, v120
	v_fmac_f32_e32 v1, s10, v121
	v_fmac_f32_e32 v2, s10, v122
	v_fmac_f32_e32 v3, s10, v123
	v_fmac_f32_e32 v4, s11, v120
	v_fmac_f32_e32 v5, s11, v121
	v_fmac_f32_e32 v6, s11, v122
	v_fmac_f32_e32 v7, s11, v123
	v_fmac_f32_e32 v8, s12, v120
	v_fmac_f32_e32 v9, s12, v121
	v_fmac_f32_e32 v10, s12, v122
	v_fmac_f32_e32 v11, s12, v123
	v_fmac_f32_e32 v12, s13, v120
	v_fmac_f32_e32 v13, s13, v121
	v_fmac_f32_e32 v14, s13, v122
	v_fmac_f32_e32 v15, s13, v123
	v_fmac_f32_e32 v16, s14, v120
	v_fmac_f32_e32 v17, s14, v121
	v_fmac_f32_e32 v18, s14, v122
	v_fmac_f32_e32 v19, s14, v123
	v_fmac_f32_e32 v20, s15, v120
	v_fmac_f32_e32 v21, s15, v121
	v_fmac_f32_e32 v22, s15, v122
	v_fmac_f32_e32 v23, s15, v123
	v_fmac_f32_e32 v24, s16, v120
	v_fmac_f32_e32 v25, s16, v121
	v_fmac_f32_e32 v26, s16, v122
	v_fmac_f32_e32 v27, s16, v123
	v_fmac_f32_e32 v28, s17, v120
	v_fmac_f32_e32 v29, s17, v121
	v_fmac_f32_e32 v30, s17, v122
	v_fmac_f32_e32 v31, s17, v123
; __device__ __forceinline__ void gemv_item(const float* c, const float* c_ctx, const float* ada_w, const float* ada_b, float* mod, int it, int lane) {
;     ...
;     for (int kk = 0; kk < 64; ++kk) { const f32x4 w = *(const f32x4*)(W + (size_t)kk * 6144);
; #pragma unroll
;         for (int r = 0; r < 9; ++r) { const float sk = __uint_as_float(__builtin_amdgcn_readlane(__float_as_uint(s[r]), kk)); acc[r] += w * sk; } }
	v_fmac_f32_e32 v32, s18, v120
	v_fmac_f32_e32 v33, s18, v121
	v_fmac_f32_e32 v34, s18, v122
	v_fmac_f32_e32 v35, s18, v123
	v_readlane_b32 s10, v36, 11
	v_readlane_b32 s11, v37, 11
	v_readlane_b32 s12, v38, 11
	v_readlane_b32 s13, v39, 11
	v_readlane_b32 s14, v40, 11
	v_readlane_b32 s15, v41, 11
	v_readlane_b32 s16, v42, 11
	v_readlane_b32 s17, v43, 11
	v_readlane_b32 s18, v44, 11
	v_fmac_f32_e32 v0, s10, v124
	v_fmac_f32_e32 v1, s10, v125
	v_fmac_f32_e32 v2, s10, v126
	v_fmac_f32_e32 v3, s10, v127
	v_fmac_f32_e32 v4, s11, v124
	v_fmac_f32_e32 v5, s11, v125
	v_fmac_f32_e32 v6, s11, v126
	v_fmac_f32_e32 v7, s11, v127
	v_fmac_f32_e32 v8, s12, v124
	v_fmac_f32_e32 v9, s12, v125
	v_fmac_f32_e32 v10, s12, v126
	v_fmac_f32_e32 v11, s12, v127
	v_fmac_f32_e32 v12, s13, v124
	v_fmac_f32_e32 v13, s13, v125
	v_fmac_f32_e32 v14, s13, v126
	v_fmac_f32_e32 v15, s13, v127
	v_fmac_f32_e32 v16, s14, v124
	v_fmac_f32_e32 v17, s14, v125
	v_fmac_f32_e32 v18, s14, v126
	v_fmac_f32_e32 v19, s14, v127
	v_fmac_f32_e32 v20, s15, v124
	v_fmac_f32_e32 v21, s15, v125
	v_fmac_f32_e32 v22, s15, v126
	v_fmac_f32_e32 v23, s15, v127
	v_fmac_f32_e32 v24, s16, v124
	v_fmac_f32_e32 v25, s16, v125
	v_fmac_f32_e32 v26, s16, v126
	v_fmac_f32_e32 v27, s16, v127
	v_fmac_f32_e32 v28, s17, v124
	v_fmac_f32_e32 v29, s17, v125
	v_fmac_f32_e32 v30, s17, v126
	v_fmac_f32_e32 v31, s17, v127
	v_fmac_f32_e32 v32, s18, v124
	v_fmac_f32_e32 v33, s18, v125
	v_fmac_f32_e32 v34, s18, v126
	v_fmac_f32_e32 v35, s18, v127
	v_readlane_b32 s10, v36, 12
	v_readlane_b32 s11, v37, 12
	v_readlane_b32 s12, v38, 12
	v_readlane_b32 s13, v39, 12
	v_readlane_b32 s14, v40, 12
	v_readlane_b32 s15, v41, 12
	v_readlane_b32 s16, v42, 12
	v_readlane_b32 s17, v43, 12
	v_readlane_b32 s18, v44, 12
	v_fmac_f32_e32 v0, s10, v128
	v_fmac_f32_e32 v1, s10, v129
	v_fmac_f32_e32 v2, s10, v130
	v_fmac_f32_e32 v3, s10, v131
	v_fmac_f32_e32 v4, s11, v128
	v_fmac_f32_e32 v5, s11, v129
	v_fmac_f32_e32 v6, s11, v130
	v_fmac_f32_e32 v7, s11, v131
	v_fmac_f32_e32 v8, s12, v128
	v_fmac_f32_e32 v9, s12, v129
	v_fmac_f32_e32 v10, s12, v130
	v_fmac_f32_e32 v11, s12, v131
	v_fmac_f32_e32 v12, s13, v128
	v_fmac_f32_e32 v13, s13, v129
	v_fmac_f32_e32 v14, s13, v130
	v_fmac_f32_e32 v15, s13, v131
	v_fmac_f32_e32 v16, s14, v128
	v_fmac_f32_e32 v17, s14, v129
	v_fmac_f32_e32 v18, s14, v130
	v_fmac_f32_e32 v19, s14, v131
	v_fmac_f32_e32 v20, s15, v128
	v_fmac_f32_e32 v21, s15, v129
	v_fmac_f32_e32 v22, s15, v130
	v_fmac_f32_e32 v23, s15, v131
	v_fmac_f32_e32 v24, s16, v128
	v_fmac_f32_e32 v25, s16, v129
	v_fmac_f32_e32 v26, s16, v130
	v_fmac_f32_e32 v27, s16, v131
	v_fmac_f32_e32 v28, s17, v128
	v_fmac_f32_e32 v29, s17, v129
	v_fmac_f32_e32 v30, s17, v130
	v_fmac_f32_e32 v31, s17, v131
	v_fmac_f32_e32 v32, s18, v128
	v_fmac_f32_e32 v33, s18, v129
	v_fmac_f32_e32 v34, s18, v130
	v_fmac_f32_e32 v35, s18, v131
	v_readlane_b32 s10, v36, 13
	v_readlane_b32 s11, v37, 13
	v_readlane_b32 s12, v38, 13
	v_readlane_b32 s13, v39, 13
	v_readlane_b32 s14, v40, 13
	v_readlane_b32 s15, v41, 13
	v_readlane_b32 s16, v42, 13
	v_readlane_b32 s17, v43, 13
	v_readlane_b32 s18, v44, 13
	v_fmac_f32_e32 v0, s10, v132
	v_fmac_f32_e32 v1, s10, v133
	v_fmac_f32_e32 v2, s10, v134
	v_fmac_f32_e32 v3, s10, v135
	v_fmac_f32_e32 v4, s11, v132
	v_fmac_f32_e32 v5, s11, v133
	v_fmac_f32_e32 v6, s11, v134
	v_fmac_f32_e32 v7, s11, v135
	v_fmac_f32_e32 v8, s12, v132
	v_fmac_f32_e32 v9, s12, v133
	v_fmac_f32_e32 v10, s12, v134
	v_fmac_f32_e32 v11, s12, v135
	v_fmac_f32_e32 v12, s13, v132
	v_fmac_f32_e32 v13, s13, v133
	v_fmac_f32_e32 v14, s13, v134
	v_fmac_f32_e32 v15, s13, v135
	v_fmac_f32_e32 v16, s14, v132
	v_fmac_f32_e32 v17, s14, v133
	v_fmac_f32_e32 v18, s14, v134
	v_fmac_f32_e32 v19, s14, v135
	v_fmac_f32_e32 v20, s15, v132
	v_fmac_f32_e32 v21, s15, v133
	v_fmac_f32_e32 v22, s15, v134
	v_fmac_f32_e32 v23, s15, v135
	v_fmac_f32_e32 v24, s16, v132
	v_fmac_f32_e32 v25, s16, v133
	v_fmac_f32_e32 v26, s16, v134
	v_fmac_f32_e32 v27, s16, v135
	v_fmac_f32_e32 v28, s17, v132
	v_fmac_f32_e32 v29, s17, v133
	v_fmac_f32_e32 v30, s17, v134
	v_fmac_f32_e32 v31, s17, v135
	v_fmac_f32_e32 v32, s18, v132
	v_fmac_f32_e32 v33, s18, v133
	v_fmac_f32_e32 v34, s18, v134
	v_fmac_f32_e32 v35, s18, v135
	v_readlane_b32 s10, v36, 14
	v_readlane_b32 s11, v37, 14
	v_readlane_b32 s12, v38, 14
	v_readlane_b32 s13, v39, 14
	v_readlane_b32 s14, v40, 14
	v_readlane_b32 s15, v41, 14
	v_readlane_b32 s16, v42, 14
	v_readlane_b32 s17, v43, 14
	v_readlane_b32 s18, v44, 14
	v_fmac_f32_e32 v0, s10, v136
	v_fmac_f32_e32 v1, s10, v137
	v_fmac_f32_e32 v2, s10, v138
	v_fmac_f32_e32 v3, s10, v139
	v_fmac_f32_e32 v4, s11, v136
	v_fmac_f32_e32 v5, s11, v137
	v_fmac_f32_e32 v6, s11, v138
	v_fmac_f32_e32 v7, s11, v139
	v_fmac_f32_e32 v8, s12, v136
	v_fmac_f32_e32 v9, s12, v137
	v_fmac_f32_e32 v10, s12, v138
	v_fmac_f32_e32 v11, s12, v139
	v_fmac_f32_e32 v12, s13, v136
	v_fmac_f32_e32 v13, s13, v137
	v_fmac_f32_e32 v14, s13, v138
	v_fmac_f32_e32 v15, s13, v139
	v_fmac_f32_e32 v16, s14, v136
	v_fmac_f32_e32 v17, s14, v137
	v_fmac_f32_e32 v18, s14, v138
	v_fmac_f32_e32 v19, s14, v139
	v_fmac_f32_e32 v20, s15, v136
	v_fmac_f32_e32 v21, s15, v137
	v_fmac_f32_e32 v22, s15, v138
	v_fmac_f32_e32 v23, s15, v139
	v_fmac_f32_e32 v24, s16, v136
	v_fmac_f32_e32 v25, s16, v137
	v_fmac_f32_e32 v26, s16, v138
	v_fmac_f32_e32 v27, s16, v139
	v_fmac_f32_e32 v28, s17, v136
	v_fmac_f32_e32 v29, s17, v137
	v_fmac_f32_e32 v30, s17, v138
	v_fmac_f32_e32 v31, s17, v139
	v_fmac_f32_e32 v32, s18, v136
	v_fmac_f32_e32 v33, s18, v137
	v_fmac_f32_e32 v34, s18, v138
	v_fmac_f32_e32 v35, s18, v139
	v_readlane_b32 s10, v36, 15
	v_readlane_b32 s11, v37, 15
; __device__ __forceinline__ void gemv_item(const float* c, const float* c_ctx, const float* ada_w, const float* ada_b, float* mod, int it, int lane) {
;     ...
;     for (int kk = 0; kk < 64; ++kk) { const f32x4 w = *(const f32x4*)(W + (size_t)kk * 6144);
; #pragma unroll
;         for (int r = 0; r < 9; ++r) { const float sk = __uint_as_float(__builtin_amdgcn_readlane(__float_as_uint(s[r]), kk)); acc[r] += w * sk; } }
	v_readlane_b32 s12, v38, 15
	v_readlane_b32 s13, v39, 15
	v_readlane_b32 s14, v40, 15
	v_readlane_b32 s15, v41, 15
	v_readlane_b32 s16, v42, 15
	v_readlane_b32 s17, v43, 15
	v_readlane_b32 s18, v44, 15
	v_fmac_f32_e32 v0, s10, v140
	v_fmac_f32_e32 v1, s10, v141
	v_fmac_f32_e32 v2, s10, v142
	v_fmac_f32_e32 v3, s10, v143
	v_fmac_f32_e32 v4, s11, v140
	v_fmac_f32_e32 v5, s11, v141
	v_fmac_f32_e32 v6, s11, v142
	v_fmac_f32_e32 v7, s11, v143
	v_fmac_f32_e32 v8, s12, v140
	v_fmac_f32_e32 v9, s12, v141
	v_fmac_f32_e32 v10, s12, v142
	v_fmac_f32_e32 v11, s12, v143
	v_fmac_f32_e32 v12, s13, v140
	v_fmac_f32_e32 v13, s13, v141
	v_fmac_f32_e32 v14, s13, v142
	v_fmac_f32_e32 v15, s13, v143
	v_fmac_f32_e32 v16, s14, v140
	v_fmac_f32_e32 v17, s14, v141
	v_fmac_f32_e32 v18, s14, v142
	v_fmac_f32_e32 v19, s14, v143
	v_fmac_f32_e32 v20, s15, v140
	v_fmac_f32_e32 v21, s15, v141
	v_fmac_f32_e32 v22, s15, v142
	v_fmac_f32_e32 v23, s15, v143
	v_fmac_f32_e32 v24, s16, v140
	v_fmac_f32_e32 v25, s16, v141
	v_fmac_f32_e32 v26, s16, v142
	v_fmac_f32_e32 v27, s16, v143
	v_fmac_f32_e32 v28, s17, v140
	v_fmac_f32_e32 v29, s17, v141
	v_fmac_f32_e32 v30, s17, v142
	v_fmac_f32_e32 v31, s17, v143
	v_fmac_f32_e32 v32, s18, v140
	v_fmac_f32_e32 v33, s18, v141
	v_fmac_f32_e32 v34, s18, v142
	v_fmac_f32_e32 v35, s18, v143
	global_load_dwordx4 v[80:83], v46, s[22:23]
	s_add_u32 s22, s22, 0x6000
	s_addc_u32 s23, s23, 0
	global_load_dwordx4 v[84:87], v46, s[22:23]
	s_add_u32 s22, s22, 0x6000
	s_addc_u32 s23, s23, 0
	global_load_dwordx4 v[88:91], v46, s[22:23]
	s_add_u32 s22, s22, 0x6000
	s_addc_u32 s23, s23, 0
	global_load_dwordx4 v[92:95], v46, s[22:23]
	s_add_u32 s22, s22, 0x6000
	s_addc_u32 s23, s23, 0
	global_load_dwordx4 v[96:99], v46, s[22:23]
	s_add_u32 s22, s22, 0x6000
	s_addc_u32 s23, s23, 0
	global_load_dwordx4 v[100:103], v46, s[22:23]
	s_add_u32 s22, s22, 0x6000
	s_addc_u32 s23, s23, 0
	global_load_dwordx4 v[104:107], v46, s[22:23]
	s_add_u32 s22, s22, 0x6000
	s_addc_u32 s23, s23, 0
	global_load_dwordx4 v[108:111], v46, s[22:23]
	s_add_u32 s22, s22, 0x6000
	s_addc_u32 s23, s23, 0
	global_load_dwordx4 v[112:115], v46, s[22:23]
	s_add_u32 s22, s22, 0x6000
	s_addc_u32 s23, s23, 0
	global_load_dwordx4 v[116:119], v46, s[22:23]
	s_add_u32 s22, s22, 0x6000
	s_addc_u32 s23, s23, 0
	global_load_dwordx4 v[120:123], v46, s[22:23]
	s_add_u32 s22, s22, 0x6000
	s_addc_u32 s23, s23, 0
	global_load_dwordx4 v[124:127], v46, s[22:23]
	s_add_u32 s22, s22, 0x6000
	s_addc_u32 s23, s23, 0
	global_load_dwordx4 v[128:131], v46, s[22:23]
	s_add_u32 s22, s22, 0x6000
	s_addc_u32 s23, s23, 0
	global_load_dwordx4 v[132:135], v46, s[22:23]
	s_add_u32 s22, s22, 0x6000
	s_addc_u32 s23, s23, 0
	global_load_dwordx4 v[136:139], v46, s[22:23]
	s_add_u32 s22, s22, 0x6000
	s_addc_u32 s23, s23, 0
	global_load_dwordx4 v[140:143], v46, s[22:23]
	s_add_u32 s22, s22, 0x6000
	s_addc_u32 s23, s23, 0
	s_waitcnt vmcnt(16)
	v_readlane_b32 s10, v36, 16
	v_readlane_b32 s11, v37, 16
	v_readlane_b32 s12, v38, 16
	v_readlane_b32 s13, v39, 16
	v_readlane_b32 s14, v40, 16
	v_readlane_b32 s15, v41, 16
	v_readlane_b32 s16, v42, 16
	v_readlane_b32 s17, v43, 16
	v_readlane_b32 s18, v44, 16
	v_fmac_f32_e32 v0, s10, v144
	v_fmac_f32_e32 v1, s10, v145
	v_fmac_f32_e32 v2, s10, v146
	v_fmac_f32_e32 v3, s10, v147
	v_fmac_f32_e32 v4, s11, v144
	v_fmac_f32_e32 v5, s11, v145
	v_fmac_f32_e32 v6, s11, v146
	v_fmac_f32_e32 v7, s11, v147
	v_fmac_f32_e32 v8, s12, v144
	v_fmac_f32_e32 v9, s12, v145
	v_fmac_f32_e32 v10, s12, v146
	v_fmac_f32_e32 v11, s12, v147
	v_fmac_f32_e32 v12, s13, v144
	v_fmac_f32_e32 v13, s13, v145
	v_fmac_f32_e32 v14, s13, v146
	v_fmac_f32_e32 v15, s13, v147
	v_fmac_f32_e32 v16, s14, v144
	v_fmac_f32_e32 v17, s14, v145
	v_fmac_f32_e32 v18, s14, v146
	v_fmac_f32_e32 v19, s14, v147
	v_fmac_f32_e32 v20, s15, v144
	v_fmac_f32_e32 v21, s15, v145
	v_fmac_f32_e32 v22, s15, v146
	v_fmac_f32_e32 v23, s15, v147
	v_fmac_f32_e32 v24, s16, v144
	v_fmac_f32_e32 v25, s16, v145
	v_fmac_f32_e32 v26, s16, v146
	v_fmac_f32_e32 v27, s16, v147
	v_fmac_f32_e32 v28, s17, v144
	v_fmac_f32_e32 v29, s17, v145
	v_fmac_f32_e32 v30, s17, v146
	v_fmac_f32_e32 v31, s17, v147
	v_fmac_f32_e32 v32, s18, v144
	v_fmac_f32_e32 v33, s18, v145
	v_fmac_f32_e32 v34, s18, v146
	v_fmac_f32_e32 v35, s18, v147
	v_readlane_b32 s10, v36, 17
	v_readlane_b32 s11, v37, 17
	v_readlane_b32 s12, v38, 17
	v_readlane_b32 s13, v39, 17
	v_readlane_b32 s14, v40, 17
	v_readlane_b32 s15, v41, 17
	v_readlane_b32 s16, v42, 17
	v_readlane_b32 s17, v43, 17
	v_readlane_b32 s18, v44, 17
	v_fmac_f32_e32 v0, s10, v148
	v_fmac_f32_e32 v1, s10, v149
	v_fmac_f32_e32 v2, s10, v150
	v_fmac_f32_e32 v3, s10, v151
	v_fmac_f32_e32 v4, s11, v148
	v_fmac_f32_e32 v5, s11, v149
	v_fmac_f32_e32 v6, s11, v150
	v_fmac_f32_e32 v7, s11, v151
	v_fmac_f32_e32 v8, s12, v148
	v_fmac_f32_e32 v9, s12, v149
	v_fmac_f32_e32 v10, s12, v150
	v_fmac_f32_e32 v11, s12, v151
	v_fmac_f32_e32 v12, s13, v148
	v_fmac_f32_e32 v13, s13, v149
	v_fmac_f32_e32 v14, s13, v150
	v_fmac_f32_e32 v15, s13, v151
	v_fmac_f32_e32 v16, s14, v148
	v_fmac_f32_e32 v17, s14, v149
	v_fmac_f32_e32 v18, s14, v150
	v_fmac_f32_e32 v19, s14, v151
	v_fmac_f32_e32 v20, s15, v148
	v_fmac_f32_e32 v21, s15, v149
	v_fmac_f32_e32 v22, s15, v150
	v_fmac_f32_e32 v23, s15, v151
	v_fmac_f32_e32 v24, s16, v148
	v_fmac_f32_e32 v25, s16, v149
	v_fmac_f32_e32 v26, s16, v150
	v_fmac_f32_e32 v27, s16, v151
	v_fmac_f32_e32 v28, s17, v148
	v_fmac_f32_e32 v29, s17, v149
	v_fmac_f32_e32 v30, s17, v150
	v_fmac_f32_e32 v31, s17, v151
	v_fmac_f32_e32 v32, s18, v148
	v_fmac_f32_e32 v33, s18, v149
	v_fmac_f32_e32 v34, s18, v150
	v_fmac_f32_e32 v35, s18, v151
; __device__ __forceinline__ void gemv_item(const float* c, const float* c_ctx, const float* ada_w, const float* ada_b, float* mod, int it, int lane) {
;     ...
;     for (int kk = 0; kk < 64; ++kk) { const f32x4 w = *(const f32x4*)(W + (size_t)kk * 6144);
; #pragma unroll
;         for (int r = 0; r < 9; ++r) { const float sk = __uint_as_float(__builtin_amdgcn_readlane(__float_as_uint(s[r]), kk)); acc[r] += w * sk; } }
	v_readlane_b32 s10, v36, 18
	v_readlane_b32 s11, v37, 18
	v_readlane_b32 s12, v38, 18
	v_readlane_b32 s13, v39, 18
	v_readlane_b32 s14, v40, 18
	v_readlane_b32 s15, v41, 18
	v_readlane_b32 s16, v42, 18
	v_readlane_b32 s17, v43, 18
	v_readlane_b32 s18, v44, 18
	v_fmac_f32_e32 v0, s10, v152
	v_fmac_f32_e32 v1, s10, v153
	v_fmac_f32_e32 v2, s10, v154
	v_fmac_f32_e32 v3, s10, v155
	v_fmac_f32_e32 v4, s11, v152
	v_fmac_f32_e32 v5, s11, v153
	v_fmac_f32_e32 v6, s11, v154
	v_fmac_f32_e32 v7, s11, v155
	v_fmac_f32_e32 v8, s12, v152
	v_fmac_f32_e32 v9, s12, v153
	v_fmac_f32_e32 v10, s12, v154
	v_fmac_f32_e32 v11, s12, v155
	v_fmac_f32_e32 v12, s13, v152
	v_fmac_f32_e32 v13, s13, v153
	v_fmac_f32_e32 v14, s13, v154
	v_fmac_f32_e32 v15, s13, v155
	v_fmac_f32_e32 v16, s14, v152
	v_fmac_f32_e32 v17, s14, v153
	v_fmac_f32_e32 v18, s14, v154
	v_fmac_f32_e32 v19, s14, v155
	v_fmac_f32_e32 v20, s15, v152
	v_fmac_f32_e32 v21, s15, v153
	v_fmac_f32_e32 v22, s15, v154
	v_fmac_f32_e32 v23, s15, v155
	v_fmac_f32_e32 v24, s16, v152
	v_fmac_f32_e32 v25, s16, v153
	v_fmac_f32_e32 v26, s16, v154
	v_fmac_f32_e32 v27, s16, v155
	v_fmac_f32_e32 v28, s17, v152
	v_fmac_f32_e32 v29, s17, v153
	v_fmac_f32_e32 v30, s17, v154
	v_fmac_f32_e32 v31, s17, v155
	v_fmac_f32_e32 v32, s18, v152
	v_fmac_f32_e32 v33, s18, v153
	v_fmac_f32_e32 v34, s18, v154
	v_fmac_f32_e32 v35, s18, v155
	v_readlane_b32 s10, v36, 19
	v_readlane_b32 s11, v37, 19
	v_readlane_b32 s12, v38, 19
	v_readlane_b32 s13, v39, 19
	v_readlane_b32 s14, v40, 19
	v_readlane_b32 s15, v41, 19
	v_readlane_b32 s16, v42, 19
	v_readlane_b32 s17, v43, 19
	v_readlane_b32 s18, v44, 19
	v_fmac_f32_e32 v0, s10, v156
	v_fmac_f32_e32 v1, s10, v157
	v_fmac_f32_e32 v2, s10, v158
	v_fmac_f32_e32 v3, s10, v159
	v_fmac_f32_e32 v4, s11, v156
	v_fmac_f32_e32 v5, s11, v157
	v_fmac_f32_e32 v6, s11, v158
	v_fmac_f32_e32 v7, s11, v159
	v_fmac_f32_e32 v8, s12, v156
	v_fmac_f32_e32 v9, s12, v157
	v_fmac_f32_e32 v10, s12, v158
	v_fmac_f32_e32 v11, s12, v159
	v_fmac_f32_e32 v12, s13, v156
	v_fmac_f32_e32 v13, s13, v157
	v_fmac_f32_e32 v14, s13, v158
	v_fmac_f32_e32 v15, s13, v159
	v_fmac_f32_e32 v16, s14, v156
	v_fmac_f32_e32 v17, s14, v157
	v_fmac_f32_e32 v18, s14, v158
	v_fmac_f32_e32 v19, s14, v159
	v_fmac_f32_e32 v20, s15, v156
	v_fmac_f32_e32 v21, s15, v157
	v_fmac_f32_e32 v22, s15, v158
	v_fmac_f32_e32 v23, s15, v159
	v_fmac_f32_e32 v24, s16, v156
	v_fmac_f32_e32 v25, s16, v157
	v_fmac_f32_e32 v26, s16, v158
	v_fmac_f32_e32 v27, s16, v159
	v_fmac_f32_e32 v28, s17, v156
	v_fmac_f32_e32 v29, s17, v157
	v_fmac_f32_e32 v30, s17, v158
	v_fmac_f32_e32 v31, s17, v159
	v_fmac_f32_e32 v32, s18, v156
	v_fmac_f32_e32 v33, s18, v157
	v_fmac_f32_e32 v34, s18, v158
	v_fmac_f32_e32 v35, s18, v159
	v_readlane_b32 s10, v36, 20
	v_readlane_b32 s11, v37, 20
	v_readlane_b32 s12, v38, 20
	v_readlane_b32 s13, v39, 20
	v_readlane_b32 s14, v40, 20
	v_readlane_b32 s15, v41, 20
	v_readlane_b32 s16, v42, 20
	v_readlane_b32 s17, v43, 20
	v_readlane_b32 s18, v44, 20
	v_fmac_f32_e32 v0, s10, v160
	v_fmac_f32_e32 v1, s10, v161
	v_fmac_f32_e32 v2, s10, v162
	v_fmac_f32_e32 v3, s10, v163
	v_fmac_f32_e32 v4, s11, v160
	v_fmac_f32_e32 v5, s11, v161
	v_fmac_f32_e32 v6, s11, v162
	v_fmac_f32_e32 v7, s11, v163
	v_fmac_f32_e32 v8, s12, v160
	v_fmac_f32_e32 v9, s12, v161
	v_fmac_f32_e32 v10, s12, v162
	v_fmac_f32_e32 v11, s12, v163
	v_fmac_f32_e32 v12, s13, v160
	v_fmac_f32_e32 v13, s13, v161
	v_fmac_f32_e32 v14, s13, v162
	v_fmac_f32_e32 v15, s13, v163
	v_fmac_f32_e32 v16, s14, v160
	v_fmac_f32_e32 v17, s14, v161
	v_fmac_f32_e32 v18, s14, v162
	v_fmac_f32_e32 v19, s14, v163
	v_fmac_f32_e32 v20, s15, v160
	v_fmac_f32_e32 v21, s15, v161
	v_fmac_f32_e32 v22, s15, v162
	v_fmac_f32_e32 v23, s15, v163
	v_fmac_f32_e32 v24, s16, v160
	v_fmac_f32_e32 v25, s16, v161
	v_fmac_f32_e32 v26, s16, v162
	v_fmac_f32_e32 v27, s16, v163
	v_fmac_f32_e32 v28, s17, v160
	v_fmac_f32_e32 v29, s17, v161
	v_fmac_f32_e32 v30, s17, v162
	v_fmac_f32_e32 v31, s17, v163
	v_fmac_f32_e32 v32, s18, v160
	v_fmac_f32_e32 v33, s18, v161
	v_fmac_f32_e32 v34, s18, v162
	v_fmac_f32_e32 v35, s18, v163
	v_readlane_b32 s10, v36, 21
	v_readlane_b32 s11, v37, 21
	v_readlane_b32 s12, v38, 21
	v_readlane_b32 s13, v39, 21
	v_readlane_b32 s14, v40, 21
	v_readlane_b32 s15, v41, 21
	v_readlane_b32 s16, v42, 21
	v_readlane_b32 s17, v43, 21
	v_readlane_b32 s18, v44, 21
	v_fmac_f32_e32 v0, s10, v164
	v_fmac_f32_e32 v1, s10, v165
	v_fmac_f32_e32 v2, s10, v166
	v_fmac_f32_e32 v3, s10, v167
	v_fmac_f32_e32 v4, s11, v164
	v_fmac_f32_e32 v5, s11, v165
	v_fmac_f32_e32 v6, s11, v166
	v_fmac_f32_e32 v7, s11, v167
	v_fmac_f32_e32 v8, s12, v164
	v_fmac_f32_e32 v9, s12, v165
	v_fmac_f32_e32 v10, s12, v166
	v_fmac_f32_e32 v11, s12, v167
	v_fmac_f32_e32 v12, s13, v164
	v_fmac_f32_e32 v13, s13, v165
	v_fmac_f32_e32 v14, s13, v166
	v_fmac_f32_e32 v15, s13, v167
	v_fmac_f32_e32 v16, s14, v164
	v_fmac_f32_e32 v17, s14, v165
	v_fmac_f32_e32 v18, s14, v166
	v_fmac_f32_e32 v19, s14, v167
	v_fmac_f32_e32 v20, s15, v164
	v_fmac_f32_e32 v21, s15, v165
	v_fmac_f32_e32 v22, s15, v166
	v_fmac_f32_e32 v23, s15, v167
	v_fmac_f32_e32 v24, s16, v164
	v_fmac_f32_e32 v25, s16, v165
	v_fmac_f32_e32 v26, s16, v166
	v_fmac_f32_e32 v27, s16, v167
	v_fmac_f32_e32 v28, s17, v164
	v_fmac_f32_e32 v29, s17, v165
	v_fmac_f32_e32 v30, s17, v166
	v_fmac_f32_e32 v31, s17, v167
	v_fmac_f32_e32 v32, s18, v164
	v_fmac_f32_e32 v33, s18, v165
	v_fmac_f32_e32 v34, s18, v166
	v_fmac_f32_e32 v35, s18, v167
	v_readlane_b32 s10, v36, 22
	v_readlane_b32 s11, v37, 22
	v_readlane_b32 s12, v38, 22
	v_readlane_b32 s13, v39, 22
	v_readlane_b32 s14, v40, 22
	v_readlane_b32 s15, v41, 22
; __device__ __forceinline__ void gemv_item(const float* c, const float* c_ctx, const float* ada_w, const float* ada_b, float* mod, int it, int lane) {
;     ...
;     for (int kk = 0; kk < 64; ++kk) { const f32x4 w = *(const f32x4*)(W + (size_t)kk * 6144);
; #pragma unroll
;         for (int r = 0; r < 9; ++r) { const float sk = __uint_as_float(__builtin_amdgcn_readlane(__float_as_uint(s[r]), kk)); acc[r] += w * sk; } }
	v_readlane_b32 s16, v42, 22
	v_readlane_b32 s17, v43, 22
	v_readlane_b32 s18, v44, 22
	v_fmac_f32_e32 v0, s10, v168
	v_fmac_f32_e32 v1, s10, v169
	v_fmac_f32_e32 v2, s10, v170
	v_fmac_f32_e32 v3, s10, v171
	v_fmac_f32_e32 v4, s11, v168
	v_fmac_f32_e32 v5, s11, v169
	v_fmac_f32_e32 v6, s11, v170
	v_fmac_f32_e32 v7, s11, v171
	v_fmac_f32_e32 v8, s12, v168
	v_fmac_f32_e32 v9, s12, v169
	v_fmac_f32_e32 v10, s12, v170
	v_fmac_f32_e32 v11, s12, v171
	v_fmac_f32_e32 v12, s13, v168
	v_fmac_f32_e32 v13, s13, v169
	v_fmac_f32_e32 v14, s13, v170
	v_fmac_f32_e32 v15, s13, v171
	v_fmac_f32_e32 v16, s14, v168
	v_fmac_f32_e32 v17, s14, v169
	v_fmac_f32_e32 v18, s14, v170
	v_fmac_f32_e32 v19, s14, v171
	v_fmac_f32_e32 v20, s15, v168
	v_fmac_f32_e32 v21, s15, v169
	v_fmac_f32_e32 v22, s15, v170
	v_fmac_f32_e32 v23, s15, v171
	v_fmac_f32_e32 v24, s16, v168
	v_fmac_f32_e32 v25, s16, v169
	v_fmac_f32_e32 v26, s16, v170
	v_fmac_f32_e32 v27, s16, v171
	v_fmac_f32_e32 v28, s17, v168
	v_fmac_f32_e32 v29, s17, v169
	v_fmac_f32_e32 v30, s17, v170
	v_fmac_f32_e32 v31, s17, v171
	v_fmac_f32_e32 v32, s18, v168
	v_fmac_f32_e32 v33, s18, v169
	v_fmac_f32_e32 v34, s18, v170
	v_fmac_f32_e32 v35, s18, v171
	v_readlane_b32 s10, v36, 23
	v_readlane_b32 s11, v37, 23
	v_readlane_b32 s12, v38, 23
	v_readlane_b32 s13, v39, 23
	v_readlane_b32 s14, v40, 23
	v_readlane_b32 s15, v41, 23
	v_readlane_b32 s16, v42, 23
	v_readlane_b32 s17, v43, 23
	v_readlane_b32 s18, v44, 23
	v_fmac_f32_e32 v0, s10, v172
	v_fmac_f32_e32 v1, s10, v173
	v_fmac_f32_e32 v2, s10, v174
	v_fmac_f32_e32 v3, s10, v175
	v_fmac_f32_e32 v4, s11, v172
	v_fmac_f32_e32 v5, s11, v173
	v_fmac_f32_e32 v6, s11, v174
	v_fmac_f32_e32 v7, s11, v175
	v_fmac_f32_e32 v8, s12, v172
	v_fmac_f32_e32 v9, s12, v173
	v_fmac_f32_e32 v10, s12, v174
	v_fmac_f32_e32 v11, s12, v175
	v_fmac_f32_e32 v12, s13, v172
	v_fmac_f32_e32 v13, s13, v173
	v_fmac_f32_e32 v14, s13, v174
	v_fmac_f32_e32 v15, s13, v175
	v_fmac_f32_e32 v16, s14, v172
	v_fmac_f32_e32 v17, s14, v173
	v_fmac_f32_e32 v18, s14, v174
	v_fmac_f32_e32 v19, s14, v175
	v_fmac_f32_e32 v20, s15, v172
	v_fmac_f32_e32 v21, s15, v173
	v_fmac_f32_e32 v22, s15, v174
	v_fmac_f32_e32 v23, s15, v175
	v_fmac_f32_e32 v24, s16, v172
	v_fmac_f32_e32 v25, s16, v173
	v_fmac_f32_e32 v26, s16, v174
	v_fmac_f32_e32 v27, s16, v175
	v_fmac_f32_e32 v28, s17, v172
	v_fmac_f32_e32 v29, s17, v173
	v_fmac_f32_e32 v30, s17, v174
	v_fmac_f32_e32 v31, s17, v175
	v_fmac_f32_e32 v32, s18, v172
	v_fmac_f32_e32 v33, s18, v173
	v_fmac_f32_e32 v34, s18, v174
	v_fmac_f32_e32 v35, s18, v175
	v_readlane_b32 s10, v36, 24
	v_readlane_b32 s11, v37, 24
	v_readlane_b32 s12, v38, 24
	v_readlane_b32 s13, v39, 24
	v_readlane_b32 s14, v40, 24
	v_readlane_b32 s15, v41, 24
	v_readlane_b32 s16, v42, 24
	v_readlane_b32 s17, v43, 24
	v_readlane_b32 s18, v44, 24
	v_fmac_f32_e32 v0, s10, v176
	v_fmac_f32_e32 v1, s10, v177
	v_fmac_f32_e32 v2, s10, v178
	v_fmac_f32_e32 v3, s10, v179
	v_fmac_f32_e32 v4, s11, v176
	v_fmac_f32_e32 v5, s11, v177
	v_fmac_f32_e32 v6, s11, v178
	v_fmac_f32_e32 v7, s11, v179
	v_fmac_f32_e32 v8, s12, v176
	v_fmac_f32_e32 v9, s12, v177
	v_fmac_f32_e32 v10, s12, v178
	v_fmac_f32_e32 v11, s12, v179
	v_fmac_f32_e32 v12, s13, v176
	v_fmac_f32_e32 v13, s13, v177
	v_fmac_f32_e32 v14, s13, v178
	v_fmac_f32_e32 v15, s13, v179
	v_fmac_f32_e32 v16, s14, v176
	v_fmac_f32_e32 v17, s14, v177
	v_fmac_f32_e32 v18, s14, v178
	v_fmac_f32_e32 v19, s14, v179
	v_fmac_f32_e32 v20, s15, v176
	v_fmac_f32_e32 v21, s15, v177
	v_fmac_f32_e32 v22, s15, v178
	v_fmac_f32_e32 v23, s15, v179
	v_fmac_f32_e32 v24, s16, v176
	v_fmac_f32_e32 v25, s16, v177
	v_fmac_f32_e32 v26, s16, v178
	v_fmac_f32_e32 v27, s16, v179
	v_fmac_f32_e32 v28, s17, v176
	v_fmac_f32_e32 v29, s17, v177
	v_fmac_f32_e32 v30, s17, v178
	v_fmac_f32_e32 v31, s17, v179
	v_fmac_f32_e32 v32, s18, v176
	v_fmac_f32_e32 v33, s18, v177
	v_fmac_f32_e32 v34, s18, v178
	v_fmac_f32_e32 v35, s18, v179
	v_readlane_b32 s10, v36, 25
	v_readlane_b32 s11, v37, 25
	v_readlane_b32 s12, v38, 25
	v_readlane_b32 s13, v39, 25
	v_readlane_b32 s14, v40, 25
	v_readlane_b32 s15, v41, 25
	v_readlane_b32 s16, v42, 25
	v_readlane_b32 s17, v43, 25
	v_readlane_b32 s18, v44, 25
	v_fmac_f32_e32 v0, s10, v180
	v_fmac_f32_e32 v1, s10, v181
	v_fmac_f32_e32 v2, s10, v182
	v_fmac_f32_e32 v3, s10, v183
	v_fmac_f32_e32 v4, s11, v180
	v_fmac_f32_e32 v5, s11, v181
	v_fmac_f32_e32 v6, s11, v182
	v_fmac_f32_e32 v7, s11, v183
	v_fmac_f32_e32 v8, s12, v180
	v_fmac_f32_e32 v9, s12, v181
	v_fmac_f32_e32 v10, s12, v182
	v_fmac_f32_e32 v11, s12, v183
	v_fmac_f32_e32 v12, s13, v180
	v_fmac_f32_e32 v13, s13, v181
	v_fmac_f32_e32 v14, s13, v182
	v_fmac_f32_e32 v15, s13, v183
	v_fmac_f32_e32 v16, s14, v180
	v_fmac_f32_e32 v17, s14, v181
	v_fmac_f32_e32 v18, s14, v182
	v_fmac_f32_e32 v19, s14, v183
	v_fmac_f32_e32 v20, s15, v180
	v_fmac_f32_e32 v21, s15, v181
	v_fmac_f32_e32 v22, s15, v182
	v_fmac_f32_e32 v23, s15, v183
	v_fmac_f32_e32 v24, s16, v180
	v_fmac_f32_e32 v25, s16, v181
	v_fmac_f32_e32 v26, s16, v182
	v_fmac_f32_e32 v27, s16, v183
	v_fmac_f32_e32 v28, s17, v180
	v_fmac_f32_e32 v29, s17, v181
	v_fmac_f32_e32 v30, s17, v182
	v_fmac_f32_e32 v31, s17, v183
	v_fmac_f32_e32 v32, s18, v180
	v_fmac_f32_e32 v33, s18, v181
	v_fmac_f32_e32 v34, s18, v182
	v_fmac_f32_e32 v35, s18, v183
	v_readlane_b32 s10, v36, 26
	v_readlane_b32 s11, v37, 26
	v_readlane_b32 s12, v38, 26
	v_readlane_b32 s13, v39, 26
	v_readlane_b32 s14, v40, 26
	v_readlane_b32 s15, v41, 26
	v_readlane_b32 s16, v42, 26
	v_readlane_b32 s17, v43, 26
	v_readlane_b32 s18, v44, 26
	v_fmac_f32_e32 v0, s10, v184
	v_fmac_f32_e32 v1, s10, v185
	v_fmac_f32_e32 v2, s10, v186
; __device__ __forceinline__ void gemv_item(const float* c, const float* c_ctx, const float* ada_w, const float* ada_b, float* mod, int it, int lane) {
;     ...
;     for (int kk = 0; kk < 64; ++kk) { const f32x4 w = *(const f32x4*)(W + (size_t)kk * 6144);
; #pragma unroll
;         for (int r = 0; r < 9; ++r) { const float sk = __uint_as_float(__builtin_amdgcn_readlane(__float_as_uint(s[r]), kk)); acc[r] += w * sk; } }
	v_fmac_f32_e32 v3, s10, v187
	v_fmac_f32_e32 v4, s11, v184
	v_fmac_f32_e32 v5, s11, v185
	v_fmac_f32_e32 v6, s11, v186
	v_fmac_f32_e32 v7, s11, v187
	v_fmac_f32_e32 v8, s12, v184
	v_fmac_f32_e32 v9, s12, v185
	v_fmac_f32_e32 v10, s12, v186
	v_fmac_f32_e32 v11, s12, v187
	v_fmac_f32_e32 v12, s13, v184
	v_fmac_f32_e32 v13, s13, v185
	v_fmac_f32_e32 v14, s13, v186
	v_fmac_f32_e32 v15, s13, v187
	v_fmac_f32_e32 v16, s14, v184
	v_fmac_f32_e32 v17, s14, v185
	v_fmac_f32_e32 v18, s14, v186
	v_fmac_f32_e32 v19, s14, v187
	v_fmac_f32_e32 v20, s15, v184
	v_fmac_f32_e32 v21, s15, v185
	v_fmac_f32_e32 v22, s15, v186
	v_fmac_f32_e32 v23, s15, v187
	v_fmac_f32_e32 v24, s16, v184
	v_fmac_f32_e32 v25, s16, v185
	v_fmac_f32_e32 v26, s16, v186
	v_fmac_f32_e32 v27, s16, v187
	v_fmac_f32_e32 v28, s17, v184
	v_fmac_f32_e32 v29, s17, v185
	v_fmac_f32_e32 v30, s17, v186
	v_fmac_f32_e32 v31, s17, v187
	v_fmac_f32_e32 v32, s18, v184
	v_fmac_f32_e32 v33, s18, v185
	v_fmac_f32_e32 v34, s18, v186
	v_fmac_f32_e32 v35, s18, v187
	v_readlane_b32 s10, v36, 27
	v_readlane_b32 s11, v37, 27
	v_readlane_b32 s12, v38, 27
	v_readlane_b32 s13, v39, 27
	v_readlane_b32 s14, v40, 27
	v_readlane_b32 s15, v41, 27
	v_readlane_b32 s16, v42, 27
	v_readlane_b32 s17, v43, 27
	v_readlane_b32 s18, v44, 27
	v_fmac_f32_e32 v0, s10, v188
	v_fmac_f32_e32 v1, s10, v189
	v_fmac_f32_e32 v2, s10, v190
	v_fmac_f32_e32 v3, s10, v191
	v_fmac_f32_e32 v4, s11, v188
	v_fmac_f32_e32 v5, s11, v189
	v_fmac_f32_e32 v6, s11, v190
	v_fmac_f32_e32 v7, s11, v191
	v_fmac_f32_e32 v8, s12, v188
	v_fmac_f32_e32 v9, s12, v189
	v_fmac_f32_e32 v10, s12, v190
	v_fmac_f32_e32 v11, s12, v191
	v_fmac_f32_e32 v12, s13, v188
	v_fmac_f32_e32 v13, s13, v189
	v_fmac_f32_e32 v14, s13, v190
	v_fmac_f32_e32 v15, s13, v191
	v_fmac_f32_e32 v16, s14, v188
	v_fmac_f32_e32 v17, s14, v189
	v_fmac_f32_e32 v18, s14, v190
	v_fmac_f32_e32 v19, s14, v191
	v_fmac_f32_e32 v20, s15, v188
	v_fmac_f32_e32 v21, s15, v189
	v_fmac_f32_e32 v22, s15, v190
	v_fmac_f32_e32 v23, s15, v191
	v_fmac_f32_e32 v24, s16, v188
	v_fmac_f32_e32 v25, s16, v189
	v_fmac_f32_e32 v26, s16, v190
	v_fmac_f32_e32 v27, s16, v191
	v_fmac_f32_e32 v28, s17, v188
	v_fmac_f32_e32 v29, s17, v189
	v_fmac_f32_e32 v30, s17, v190
	v_fmac_f32_e32 v31, s17, v191
	v_fmac_f32_e32 v32, s18, v188
	v_fmac_f32_e32 v33, s18, v189
	v_fmac_f32_e32 v34, s18, v190
	v_fmac_f32_e32 v35, s18, v191
	v_readlane_b32 s10, v36, 28
	v_readlane_b32 s11, v37, 28
	v_readlane_b32 s12, v38, 28
	v_readlane_b32 s13, v39, 28
	v_readlane_b32 s14, v40, 28
	v_readlane_b32 s15, v41, 28
	v_readlane_b32 s16, v42, 28
	v_readlane_b32 s17, v43, 28
	v_readlane_b32 s18, v44, 28
	v_fmac_f32_e32 v0, s10, v192
	v_fmac_f32_e32 v1, s10, v193
	v_fmac_f32_e32 v2, s10, v194
	v_fmac_f32_e32 v3, s10, v195
	v_fmac_f32_e32 v4, s11, v192
	v_fmac_f32_e32 v5, s11, v193
	v_fmac_f32_e32 v6, s11, v194
	v_fmac_f32_e32 v7, s11, v195
	v_fmac_f32_e32 v8, s12, v192
	v_fmac_f32_e32 v9, s12, v193
	v_fmac_f32_e32 v10, s12, v194
	v_fmac_f32_e32 v11, s12, v195
	v_fmac_f32_e32 v12, s13, v192
	v_fmac_f32_e32 v13, s13, v193
	v_fmac_f32_e32 v14, s13, v194
	v_fmac_f32_e32 v15, s13, v195
	v_fmac_f32_e32 v16, s14, v192
	v_fmac_f32_e32 v17, s14, v193
	v_fmac_f32_e32 v18, s14, v194
	v_fmac_f32_e32 v19, s14, v195
	v_fmac_f32_e32 v20, s15, v192
	v_fmac_f32_e32 v21, s15, v193
	v_fmac_f32_e32 v22, s15, v194
	v_fmac_f32_e32 v23, s15, v195
	v_fmac_f32_e32 v24, s16, v192
	v_fmac_f32_e32 v25, s16, v193
	v_fmac_f32_e32 v26, s16, v194
	v_fmac_f32_e32 v27, s16, v195
	v_fmac_f32_e32 v28, s17, v192
	v_fmac_f32_e32 v29, s17, v193
	v_fmac_f32_e32 v30, s17, v194
	v_fmac_f32_e32 v31, s17, v195
	v_fmac_f32_e32 v32, s18, v192
	v_fmac_f32_e32 v33, s18, v193
	v_fmac_f32_e32 v34, s18, v194
	v_fmac_f32_e32 v35, s18, v195
	v_readlane_b32 s10, v36, 29
	v_readlane_b32 s11, v37, 29
	v_readlane_b32 s12, v38, 29
	v_readlane_b32 s13, v39, 29
	v_readlane_b32 s14, v40, 29
	v_readlane_b32 s15, v41, 29
	v_readlane_b32 s16, v42, 29
	v_readlane_b32 s17, v43, 29
	v_readlane_b32 s18, v44, 29
	v_fmac_f32_e32 v0, s10, v200
	v_fmac_f32_e32 v1, s10, v201
	v_fmac_f32_e32 v2, s10, v202
	v_fmac_f32_e32 v3, s10, v203
	v_fmac_f32_e32 v4, s11, v200
	v_fmac_f32_e32 v5, s11, v201
	v_fmac_f32_e32 v6, s11, v202
	v_fmac_f32_e32 v7, s11, v203
	v_fmac_f32_e32 v8, s12, v200
	v_fmac_f32_e32 v9, s12, v201
	v_fmac_f32_e32 v10, s12, v202
	v_fmac_f32_e32 v11, s12, v203
	v_fmac_f32_e32 v12, s13, v200
	v_fmac_f32_e32 v13, s13, v201
	v_fmac_f32_e32 v14, s13, v202
	v_fmac_f32_e32 v15, s13, v203
	v_fmac_f32_e32 v16, s14, v200
	v_fmac_f32_e32 v17, s14, v201
	v_fmac_f32_e32 v18, s14, v202
	v_fmac_f32_e32 v19, s14, v203
	v_fmac_f32_e32 v20, s15, v200
	v_fmac_f32_e32 v21, s15, v201
	v_fmac_f32_e32 v22, s15, v202
	v_fmac_f32_e32 v23, s15, v203
	v_fmac_f32_e32 v24, s16, v200
	v_fmac_f32_e32 v25, s16, v201
	v_fmac_f32_e32 v26, s16, v202
	v_fmac_f32_e32 v27, s16, v203
	v_fmac_f32_e32 v28, s17, v200
	v_fmac_f32_e32 v29, s17, v201
	v_fmac_f32_e32 v30, s17, v202
	v_fmac_f32_e32 v31, s17, v203
	v_fmac_f32_e32 v32, s18, v200
	v_fmac_f32_e32 v33, s18, v201
	v_fmac_f32_e32 v34, s18, v202
	v_fmac_f32_e32 v35, s18, v203
	v_readlane_b32 s10, v36, 30
	v_readlane_b32 s11, v37, 30
	v_readlane_b32 s12, v38, 30
	v_readlane_b32 s13, v39, 30
	v_readlane_b32 s14, v40, 30
	v_readlane_b32 s15, v41, 30
	v_readlane_b32 s16, v42, 30
	v_readlane_b32 s17, v43, 30
	v_readlane_b32 s18, v44, 30
	v_fmac_f32_e32 v0, s10, v204
	v_fmac_f32_e32 v1, s10, v205
	v_fmac_f32_e32 v2, s10, v206
	v_fmac_f32_e32 v3, s10, v207
	v_fmac_f32_e32 v4, s11, v204
	v_fmac_f32_e32 v5, s11, v205
	v_fmac_f32_e32 v6, s11, v206
	v_fmac_f32_e32 v7, s11, v207
	v_fmac_f32_e32 v8, s12, v204
; __device__ __forceinline__ void gemv_item(const float* c, const float* c_ctx, const float* ada_w, const float* ada_b, float* mod, int it, int lane) {
;     ...
;     for (int kk = 0; kk < 64; ++kk) { const f32x4 w = *(const f32x4*)(W + (size_t)kk * 6144);
; #pragma unroll
;         for (int r = 0; r < 9; ++r) { const float sk = __uint_as_float(__builtin_amdgcn_readlane(__float_as_uint(s[r]), kk)); acc[r] += w * sk; } }
	v_fmac_f32_e32 v9, s12, v205
	v_fmac_f32_e32 v10, s12, v206
	v_fmac_f32_e32 v11, s12, v207
	v_fmac_f32_e32 v12, s13, v204
	v_fmac_f32_e32 v13, s13, v205
	v_fmac_f32_e32 v14, s13, v206
	v_fmac_f32_e32 v15, s13, v207
	v_fmac_f32_e32 v16, s14, v204
	v_fmac_f32_e32 v17, s14, v205
	v_fmac_f32_e32 v18, s14, v206
	v_fmac_f32_e32 v19, s14, v207
	v_fmac_f32_e32 v20, s15, v204
	v_fmac_f32_e32 v21, s15, v205
	v_fmac_f32_e32 v22, s15, v206
	v_fmac_f32_e32 v23, s15, v207
	v_fmac_f32_e32 v24, s16, v204
	v_fmac_f32_e32 v25, s16, v205
	v_fmac_f32_e32 v26, s16, v206
	v_fmac_f32_e32 v27, s16, v207
	v_fmac_f32_e32 v28, s17, v204
	v_fmac_f32_e32 v29, s17, v205
	v_fmac_f32_e32 v30, s17, v206
	v_fmac_f32_e32 v31, s17, v207
	v_fmac_f32_e32 v32, s18, v204
	v_fmac_f32_e32 v33, s18, v205
	v_fmac_f32_e32 v34, s18, v206
	v_fmac_f32_e32 v35, s18, v207
	v_readlane_b32 s10, v36, 31
	v_readlane_b32 s11, v37, 31
	v_readlane_b32 s12, v38, 31
	v_readlane_b32 s13, v39, 31
	v_readlane_b32 s14, v40, 31
	v_readlane_b32 s15, v41, 31
	v_readlane_b32 s16, v42, 31
	v_readlane_b32 s17, v43, 31
	v_readlane_b32 s18, v44, 31
	v_fmac_f32_e32 v0, s10, v208
	v_fmac_f32_e32 v1, s10, v209
	v_fmac_f32_e32 v2, s10, v210
	v_fmac_f32_e32 v3, s10, v211
	v_fmac_f32_e32 v4, s11, v208
	v_fmac_f32_e32 v5, s11, v209
	v_fmac_f32_e32 v6, s11, v210
	v_fmac_f32_e32 v7, s11, v211
	v_fmac_f32_e32 v8, s12, v208
	v_fmac_f32_e32 v9, s12, v209
	v_fmac_f32_e32 v10, s12, v210
	v_fmac_f32_e32 v11, s12, v211
	v_fmac_f32_e32 v12, s13, v208
	v_fmac_f32_e32 v13, s13, v209
	v_fmac_f32_e32 v14, s13, v210
	v_fmac_f32_e32 v15, s13, v211
	v_fmac_f32_e32 v16, s14, v208
	v_fmac_f32_e32 v17, s14, v209
	v_fmac_f32_e32 v18, s14, v210
	v_fmac_f32_e32 v19, s14, v211
	v_fmac_f32_e32 v20, s15, v208
	v_fmac_f32_e32 v21, s15, v209
	v_fmac_f32_e32 v22, s15, v210
	v_fmac_f32_e32 v23, s15, v211
	v_fmac_f32_e32 v24, s16, v208
	v_fmac_f32_e32 v25, s16, v209
	v_fmac_f32_e32 v26, s16, v210
	v_fmac_f32_e32 v27, s16, v211
	v_fmac_f32_e32 v28, s17, v208
	v_fmac_f32_e32 v29, s17, v209
	v_fmac_f32_e32 v30, s17, v210
	v_fmac_f32_e32 v31, s17, v211
	v_fmac_f32_e32 v32, s18, v208
	v_fmac_f32_e32 v33, s18, v209
	v_fmac_f32_e32 v34, s18, v210
	v_fmac_f32_e32 v35, s18, v211
	global_load_dwordx4 v[144:147], v46, s[22:23]
	s_add_u32 s22, s22, 0x6000
	s_addc_u32 s23, s23, 0
	global_load_dwordx4 v[148:151], v46, s[22:23]
	s_add_u32 s22, s22, 0x6000
	s_addc_u32 s23, s23, 0
	global_load_dwordx4 v[152:155], v46, s[22:23]
	s_add_u32 s22, s22, 0x6000
	s_addc_u32 s23, s23, 0
	global_load_dwordx4 v[156:159], v46, s[22:23]
	s_add_u32 s22, s22, 0x6000
	s_addc_u32 s23, s23, 0
	global_load_dwordx4 v[160:163], v46, s[22:23]
	s_add_u32 s22, s22, 0x6000
	s_addc_u32 s23, s23, 0
	global_load_dwordx4 v[164:167], v46, s[22:23]
	s_add_u32 s22, s22, 0x6000
	s_addc_u32 s23, s23, 0
	global_load_dwordx4 v[168:171], v46, s[22:23]
	s_add_u32 s22, s22, 0x6000
	s_addc_u32 s23, s23, 0
	global_load_dwordx4 v[172:175], v46, s[22:23]
	s_add_u32 s22, s22, 0x6000
	s_addc_u32 s23, s23, 0
	global_load_dwordx4 v[176:179], v46, s[22:23]
	s_add_u32 s22, s22, 0x6000
	s_addc_u32 s23, s23, 0
	global_load_dwordx4 v[180:183], v46, s[22:23]
	s_add_u32 s22, s22, 0x6000
	s_addc_u32 s23, s23, 0
	global_load_dwordx4 v[184:187], v46, s[22:23]
	s_add_u32 s22, s22, 0x6000
	s_addc_u32 s23, s23, 0
	global_load_dwordx4 v[188:191], v46, s[22:23]
	s_add_u32 s22, s22, 0x6000
	s_addc_u32 s23, s23, 0
	global_load_dwordx4 v[192:195], v46, s[22:23]
	s_add_u32 s22, s22, 0x6000
	s_addc_u32 s23, s23, 0
	global_load_dwordx4 v[200:203], v46, s[22:23]
	s_add_u32 s22, s22, 0x6000
	s_addc_u32 s23, s23, 0
	global_load_dwordx4 v[204:207], v46, s[22:23]
	s_add_u32 s22, s22, 0x6000
	s_addc_u32 s23, s23, 0
	global_load_dwordx4 v[208:211], v46, s[22:23]
	s_add_u32 s22, s22, 0x6000
	s_addc_u32 s23, s23, 0
	s_waitcnt vmcnt(16)
	v_readlane_b32 s10, v36, 32
	v_readlane_b32 s11, v37, 32
	v_readlane_b32 s12, v38, 32
	v_readlane_b32 s13, v39, 32
	v_readlane_b32 s14, v40, 32
	v_readlane_b32 s15, v41, 32
	v_readlane_b32 s16, v42, 32
	v_readlane_b32 s17, v43, 32
	v_readlane_b32 s18, v44, 32
	v_fmac_f32_e32 v0, s10, v80
	v_fmac_f32_e32 v1, s10, v81
	v_fmac_f32_e32 v2, s10, v82
	v_fmac_f32_e32 v3, s10, v83
	v_fmac_f32_e32 v4, s11, v80
	v_fmac_f32_e32 v5, s11, v81
	v_fmac_f32_e32 v6, s11, v82
	v_fmac_f32_e32 v7, s11, v83
	v_fmac_f32_e32 v8, s12, v80
	v_fmac_f32_e32 v9, s12, v81
	v_fmac_f32_e32 v10, s12, v82
	v_fmac_f32_e32 v11, s12, v83
	v_fmac_f32_e32 v12, s13, v80
	v_fmac_f32_e32 v13, s13, v81
	v_fmac_f32_e32 v14, s13, v82
	v_fmac_f32_e32 v15, s13, v83
	v_fmac_f32_e32 v16, s14, v80
	v_fmac_f32_e32 v17, s14, v81
	v_fmac_f32_e32 v18, s14, v82
	v_fmac_f32_e32 v19, s14, v83
	v_fmac_f32_e32 v20, s15, v80
	v_fmac_f32_e32 v21, s15, v81
	v_fmac_f32_e32 v22, s15, v82
	v_fmac_f32_e32 v23, s15, v83
	v_fmac_f32_e32 v24, s16, v80
	v_fmac_f32_e32 v25, s16, v81
	v_fmac_f32_e32 v26, s16, v82
	v_fmac_f32_e32 v27, s16, v83
	v_fmac_f32_e32 v28, s17, v80
	v_fmac_f32_e32 v29, s17, v81
	v_fmac_f32_e32 v30, s17, v82
	v_fmac_f32_e32 v31, s17, v83
	v_fmac_f32_e32 v32, s18, v80
	v_fmac_f32_e32 v33, s18, v81
	v_fmac_f32_e32 v34, s18, v82
	v_fmac_f32_e32 v35, s18, v83
	v_readlane_b32 s10, v36, 33
	v_readlane_b32 s11, v37, 33
	v_readlane_b32 s12, v38, 33
	v_readlane_b32 s13, v39, 33
	v_readlane_b32 s14, v40, 33
	v_readlane_b32 s15, v41, 33
	v_readlane_b32 s16, v42, 33
	v_readlane_b32 s17, v43, 33
	v_readlane_b32 s18, v44, 33
	v_fmac_f32_e32 v0, s10, v84
	v_fmac_f32_e32 v1, s10, v85
	v_fmac_f32_e32 v2, s10, v86
	v_fmac_f32_e32 v3, s10, v87
	v_fmac_f32_e32 v4, s11, v84
	v_fmac_f32_e32 v5, s11, v85
	v_fmac_f32_e32 v6, s11, v86
	v_fmac_f32_e32 v7, s11, v87
; __device__ __forceinline__ void gemv_item(const float* c, const float* c_ctx, const float* ada_w, const float* ada_b, float* mod, int it, int lane) {
;     ...
;     for (int kk = 0; kk < 64; ++kk) { const f32x4 w = *(const f32x4*)(W + (size_t)kk * 6144);
; #pragma unroll
;         for (int r = 0; r < 9; ++r) { const float sk = __uint_as_float(__builtin_amdgcn_readlane(__float_as_uint(s[r]), kk)); acc[r] += w * sk; } }
	v_fmac_f32_e32 v8, s12, v84
	v_fmac_f32_e32 v9, s12, v85
	v_fmac_f32_e32 v10, s12, v86
	v_fmac_f32_e32 v11, s12, v87
	v_fmac_f32_e32 v12, s13, v84
	v_fmac_f32_e32 v13, s13, v85
	v_fmac_f32_e32 v14, s13, v86
	v_fmac_f32_e32 v15, s13, v87
	v_fmac_f32_e32 v16, s14, v84
	v_fmac_f32_e32 v17, s14, v85
	v_fmac_f32_e32 v18, s14, v86
	v_fmac_f32_e32 v19, s14, v87
	v_fmac_f32_e32 v20, s15, v84
	v_fmac_f32_e32 v21, s15, v85
	v_fmac_f32_e32 v22, s15, v86
	v_fmac_f32_e32 v23, s15, v87
	v_fmac_f32_e32 v24, s16, v84
	v_fmac_f32_e32 v25, s16, v85
	v_fmac_f32_e32 v26, s16, v86
	v_fmac_f32_e32 v27, s16, v87
	v_fmac_f32_e32 v28, s17, v84
	v_fmac_f32_e32 v29, s17, v85
	v_fmac_f32_e32 v30, s17, v86
	v_fmac_f32_e32 v31, s17, v87
	v_fmac_f32_e32 v32, s18, v84
	v_fmac_f32_e32 v33, s18, v85
	v_fmac_f32_e32 v34, s18, v86
	v_fmac_f32_e32 v35, s18, v87
	v_readlane_b32 s10, v36, 34
	v_readlane_b32 s11, v37, 34
	v_readlane_b32 s12, v38, 34
	v_readlane_b32 s13, v39, 34
	v_readlane_b32 s14, v40, 34
	v_readlane_b32 s15, v41, 34
	v_readlane_b32 s16, v42, 34
	v_readlane_b32 s17, v43, 34
	v_readlane_b32 s18, v44, 34
	v_fmac_f32_e32 v0, s10, v88
	v_fmac_f32_e32 v1, s10, v89
	v_fmac_f32_e32 v2, s10, v90
	v_fmac_f32_e32 v3, s10, v91
	v_fmac_f32_e32 v4, s11, v88
	v_fmac_f32_e32 v5, s11, v89
	v_fmac_f32_e32 v6, s11, v90
	v_fmac_f32_e32 v7, s11, v91
	v_fmac_f32_e32 v8, s12, v88
	v_fmac_f32_e32 v9, s12, v89
	v_fmac_f32_e32 v10, s12, v90
	v_fmac_f32_e32 v11, s12, v91
	v_fmac_f32_e32 v12, s13, v88
	v_fmac_f32_e32 v13, s13, v89
	v_fmac_f32_e32 v14, s13, v90
	v_fmac_f32_e32 v15, s13, v91
	v_fmac_f32_e32 v16, s14, v88
	v_fmac_f32_e32 v17, s14, v89
	v_fmac_f32_e32 v18, s14, v90
	v_fmac_f32_e32 v19, s14, v91
	v_fmac_f32_e32 v20, s15, v88
	v_fmac_f32_e32 v21, s15, v89
	v_fmac_f32_e32 v22, s15, v90
	v_fmac_f32_e32 v23, s15, v91
	v_fmac_f32_e32 v24, s16, v88
	v_fmac_f32_e32 v25, s16, v89
	v_fmac_f32_e32 v26, s16, v90
	v_fmac_f32_e32 v27, s16, v91
	v_fmac_f32_e32 v28, s17, v88
	v_fmac_f32_e32 v29, s17, v89
	v_fmac_f32_e32 v30, s17, v90
	v_fmac_f32_e32 v31, s17, v91
	v_fmac_f32_e32 v32, s18, v88
	v_fmac_f32_e32 v33, s18, v89
	v_fmac_f32_e32 v34, s18, v90
	v_fmac_f32_e32 v35, s18, v91
	v_readlane_b32 s10, v36, 35
	v_readlane_b32 s11, v37, 35
	v_readlane_b32 s12, v38, 35
	v_readlane_b32 s13, v39, 35
	v_readlane_b32 s14, v40, 35
	v_readlane_b32 s15, v41, 35
	v_readlane_b32 s16, v42, 35
	v_readlane_b32 s17, v43, 35
	v_readlane_b32 s18, v44, 35
	v_fmac_f32_e32 v0, s10, v92
	v_fmac_f32_e32 v1, s10, v93
	v_fmac_f32_e32 v2, s10, v94
	v_fmac_f32_e32 v3, s10, v95
	v_fmac_f32_e32 v4, s11, v92
	v_fmac_f32_e32 v5, s11, v93
	v_fmac_f32_e32 v6, s11, v94
	v_fmac_f32_e32 v7, s11, v95
	v_fmac_f32_e32 v8, s12, v92
	v_fmac_f32_e32 v9, s12, v93
	v_fmac_f32_e32 v10, s12, v94
	v_fmac_f32_e32 v11, s12, v95
	v_fmac_f32_e32 v12, s13, v92
	v_fmac_f32_e32 v13, s13, v93
	v_fmac_f32_e32 v14, s13, v94
	v_fmac_f32_e32 v15, s13, v95
	v_fmac_f32_e32 v16, s14, v92
	v_fmac_f32_e32 v17, s14, v93
	v_fmac_f32_e32 v18, s14, v94
	v_fmac_f32_e32 v19, s14, v95
	v_fmac_f32_e32 v20, s15, v92
	v_fmac_f32_e32 v21, s15, v93
	v_fmac_f32_e32 v22, s15, v94
	v_fmac_f32_e32 v23, s15, v95
	v_fmac_f32_e32 v24, s16, v92
	v_fmac_f32_e32 v25, s16, v93
	v_fmac_f32_e32 v26, s16, v94
	v_fmac_f32_e32 v27, s16, v95
	v_fmac_f32_e32 v28, s17, v92
	v_fmac_f32_e32 v29, s17, v93
	v_fmac_f32_e32 v30, s17, v94
	v_fmac_f32_e32 v31, s17, v95
	v_fmac_f32_e32 v32, s18, v92
	v_fmac_f32_e32 v33, s18, v93
	v_fmac_f32_e32 v34, s18, v94
	v_fmac_f32_e32 v35, s18, v95
	v_readlane_b32 s10, v36, 36
	v_readlane_b32 s11, v37, 36
	v_readlane_b32 s12, v38, 36
	v_readlane_b32 s13, v39, 36
	v_readlane_b32 s14, v40, 36
	v_readlane_b32 s15, v41, 36
	v_readlane_b32 s16, v42, 36
	v_readlane_b32 s17, v43, 36
	v_readlane_b32 s18, v44, 36
	v_fmac_f32_e32 v0, s10, v96
	v_fmac_f32_e32 v1, s10, v97
	v_fmac_f32_e32 v2, s10, v98
	v_fmac_f32_e32 v3, s10, v99
	v_fmac_f32_e32 v4, s11, v96
	v_fmac_f32_e32 v5, s11, v97
	v_fmac_f32_e32 v6, s11, v98
	v_fmac_f32_e32 v7, s11, v99
	v_fmac_f32_e32 v8, s12, v96
	v_fmac_f32_e32 v9, s12, v97
	v_fmac_f32_e32 v10, s12, v98
	v_fmac_f32_e32 v11, s12, v99
	v_fmac_f32_e32 v12, s13, v96
	v_fmac_f32_e32 v13, s13, v97
	v_fmac_f32_e32 v14, s13, v98
	v_fmac_f32_e32 v15, s13, v99
	v_fmac_f32_e32 v16, s14, v96
	v_fmac_f32_e32 v17, s14, v97
	v_fmac_f32_e32 v18, s14, v98
	v_fmac_f32_e32 v19, s14, v99
	v_fmac_f32_e32 v20, s15, v96
	v_fmac_f32_e32 v21, s15, v97
	v_fmac_f32_e32 v22, s15, v98
	v_fmac_f32_e32 v23, s15, v99
	v_fmac_f32_e32 v24, s16, v96
	v_fmac_f32_e32 v25, s16, v97
	v_fmac_f32_e32 v26, s16, v98
	v_fmac_f32_e32 v27, s16, v99
	v_fmac_f32_e32 v28, s17, v96
	v_fmac_f32_e32 v29, s17, v97
	v_fmac_f32_e32 v30, s17, v98
	v_fmac_f32_e32 v31, s17, v99
	v_fmac_f32_e32 v32, s18, v96
	v_fmac_f32_e32 v33, s18, v97
	v_fmac_f32_e32 v34, s18, v98
	v_fmac_f32_e32 v35, s18, v99
	v_readlane_b32 s10, v36, 37
	v_readlane_b32 s11, v37, 37
	v_readlane_b32 s12, v38, 37
	v_readlane_b32 s13, v39, 37
	v_readlane_b32 s14, v40, 37
	v_readlane_b32 s15, v41, 37
	v_readlane_b32 s16, v42, 37
	v_readlane_b32 s17, v43, 37
	v_readlane_b32 s18, v44, 37
	v_fmac_f32_e32 v0, s10, v100
	v_fmac_f32_e32 v1, s10, v101
	v_fmac_f32_e32 v2, s10, v102
	v_fmac_f32_e32 v3, s10, v103
	v_fmac_f32_e32 v4, s11, v100
	v_fmac_f32_e32 v5, s11, v101
	v_fmac_f32_e32 v6, s11, v102
	v_fmac_f32_e32 v7, s11, v103
	v_fmac_f32_e32 v8, s12, v100
	v_fmac_f32_e32 v9, s12, v101
	v_fmac_f32_e32 v10, s12, v102
	v_fmac_f32_e32 v11, s12, v103
	v_fmac_f32_e32 v12, s13, v100
	v_fmac_f32_e32 v13, s13, v101
	v_fmac_f32_e32 v14, s13, v102
	v_fmac_f32_e32 v15, s13, v103
	v_fmac_f32_e32 v16, s14, v100
	v_fmac_f32_e32 v17, s14, v101
; __device__ __forceinline__ void gemv_item(const float* c, const float* c_ctx, const float* ada_w, const float* ada_b, float* mod, int it, int lane) {
;     ...
;     for (int kk = 0; kk < 64; ++kk) { const f32x4 w = *(const f32x4*)(W + (size_t)kk * 6144);
; #pragma unroll
;         for (int r = 0; r < 9; ++r) { const float sk = __uint_as_float(__builtin_amdgcn_readlane(__float_as_uint(s[r]), kk)); acc[r] += w * sk; } }
	v_fmac_f32_e32 v18, s14, v102
	v_fmac_f32_e32 v19, s14, v103
	v_fmac_f32_e32 v20, s15, v100
	v_fmac_f32_e32 v21, s15, v101
	v_fmac_f32_e32 v22, s15, v102
	v_fmac_f32_e32 v23, s15, v103
	v_fmac_f32_e32 v24, s16, v100
	v_fmac_f32_e32 v25, s16, v101
	v_fmac_f32_e32 v26, s16, v102
	v_fmac_f32_e32 v27, s16, v103
	v_fmac_f32_e32 v28, s17, v100
	v_fmac_f32_e32 v29, s17, v101
	v_fmac_f32_e32 v30, s17, v102
	v_fmac_f32_e32 v31, s17, v103
	v_fmac_f32_e32 v32, s18, v100
	v_fmac_f32_e32 v33, s18, v101
	v_fmac_f32_e32 v34, s18, v102
	v_fmac_f32_e32 v35, s18, v103
	v_readlane_b32 s10, v36, 38
	v_readlane_b32 s11, v37, 38
	v_readlane_b32 s12, v38, 38
	v_readlane_b32 s13, v39, 38
	v_readlane_b32 s14, v40, 38
	v_readlane_b32 s15, v41, 38
	v_readlane_b32 s16, v42, 38
	v_readlane_b32 s17, v43, 38
	v_readlane_b32 s18, v44, 38
	v_fmac_f32_e32 v0, s10, v104
	v_fmac_f32_e32 v1, s10, v105
	v_fmac_f32_e32 v2, s10, v106
	v_fmac_f32_e32 v3, s10, v107
	v_fmac_f32_e32 v4, s11, v104
	v_fmac_f32_e32 v5, s11, v105
	v_fmac_f32_e32 v6, s11, v106
	v_fmac_f32_e32 v7, s11, v107
	v_fmac_f32_e32 v8, s12, v104
	v_fmac_f32_e32 v9, s12, v105
	v_fmac_f32_e32 v10, s12, v106
	v_fmac_f32_e32 v11, s12, v107
	v_fmac_f32_e32 v12, s13, v104
	v_fmac_f32_e32 v13, s13, v105
	v_fmac_f32_e32 v14, s13, v106
	v_fmac_f32_e32 v15, s13, v107
	v_fmac_f32_e32 v16, s14, v104
	v_fmac_f32_e32 v17, s14, v105
	v_fmac_f32_e32 v18, s14, v106
	v_fmac_f32_e32 v19, s14, v107
	v_fmac_f32_e32 v20, s15, v104
	v_fmac_f32_e32 v21, s15, v105
	v_fmac_f32_e32 v22, s15, v106
	v_fmac_f32_e32 v23, s15, v107
	v_fmac_f32_e32 v24, s16, v104
	v_fmac_f32_e32 v25, s16, v105
	v_fmac_f32_e32 v26, s16, v106
	v_fmac_f32_e32 v27, s16, v107
	v_fmac_f32_e32 v28, s17, v104
	v_fmac_f32_e32 v29, s17, v105
	v_fmac_f32_e32 v30, s17, v106
	v_fmac_f32_e32 v31, s17, v107
	v_fmac_f32_e32 v32, s18, v104
	v_fmac_f32_e32 v33, s18, v105
	v_fmac_f32_e32 v34, s18, v106
	v_fmac_f32_e32 v35, s18, v107
	v_readlane_b32 s10, v36, 39
	v_readlane_b32 s11, v37, 39
	v_readlane_b32 s12, v38, 39
	v_readlane_b32 s13, v39, 39
	v_readlane_b32 s14, v40, 39
	v_readlane_b32 s15, v41, 39
	v_readlane_b32 s16, v42, 39
	v_readlane_b32 s17, v43, 39
	v_readlane_b32 s18, v44, 39
	v_fmac_f32_e32 v0, s10, v108
	v_fmac_f32_e32 v1, s10, v109
	v_fmac_f32_e32 v2, s10, v110
	v_fmac_f32_e32 v3, s10, v111
	v_fmac_f32_e32 v4, s11, v108
	v_fmac_f32_e32 v5, s11, v109
	v_fmac_f32_e32 v6, s11, v110
	v_fmac_f32_e32 v7, s11, v111
	v_fmac_f32_e32 v8, s12, v108
	v_fmac_f32_e32 v9, s12, v109
	v_fmac_f32_e32 v10, s12, v110
	v_fmac_f32_e32 v11, s12, v111
	v_fmac_f32_e32 v12, s13, v108
	v_fmac_f32_e32 v13, s13, v109
	v_fmac_f32_e32 v14, s13, v110
	v_fmac_f32_e32 v15, s13, v111
	v_fmac_f32_e32 v16, s14, v108
	v_fmac_f32_e32 v17, s14, v109
	v_fmac_f32_e32 v18, s14, v110
	v_fmac_f32_e32 v19, s14, v111
	v_fmac_f32_e32 v20, s15, v108
	v_fmac_f32_e32 v21, s15, v109
	v_fmac_f32_e32 v22, s15, v110
	v_fmac_f32_e32 v23, s15, v111
	v_fmac_f32_e32 v24, s16, v108
	v_fmac_f32_e32 v25, s16, v109
	v_fmac_f32_e32 v26, s16, v110
	v_fmac_f32_e32 v27, s16, v111
	v_fmac_f32_e32 v28, s17, v108
	v_fmac_f32_e32 v29, s17, v109
	v_fmac_f32_e32 v30, s17, v110
	v_fmac_f32_e32 v31, s17, v111
	v_fmac_f32_e32 v32, s18, v108
	v_fmac_f32_e32 v33, s18, v109
	v_fmac_f32_e32 v34, s18, v110
	v_fmac_f32_e32 v35, s18, v111
	v_readlane_b32 s10, v36, 40
	v_readlane_b32 s11, v37, 40
	v_readlane_b32 s12, v38, 40
	v_readlane_b32 s13, v39, 40
	v_readlane_b32 s14, v40, 40
	v_readlane_b32 s15, v41, 40
	v_readlane_b32 s16, v42, 40
	v_readlane_b32 s17, v43, 40
	v_readlane_b32 s18, v44, 40
	v_fmac_f32_e32 v0, s10, v112
	v_fmac_f32_e32 v1, s10, v113
	v_fmac_f32_e32 v2, s10, v114
	v_fmac_f32_e32 v3, s10, v115
	v_fmac_f32_e32 v4, s11, v112
	v_fmac_f32_e32 v5, s11, v113
	v_fmac_f32_e32 v6, s11, v114
	v_fmac_f32_e32 v7, s11, v115
	v_fmac_f32_e32 v8, s12, v112
	v_fmac_f32_e32 v9, s12, v113
	v_fmac_f32_e32 v10, s12, v114
	v_fmac_f32_e32 v11, s12, v115
	v_fmac_f32_e32 v12, s13, v112
	v_fmac_f32_e32 v13, s13, v113
	v_fmac_f32_e32 v14, s13, v114
	v_fmac_f32_e32 v15, s13, v115
	v_fmac_f32_e32 v16, s14, v112
	v_fmac_f32_e32 v17, s14, v113
	v_fmac_f32_e32 v18, s14, v114
	v_fmac_f32_e32 v19, s14, v115
	v_fmac_f32_e32 v20, s15, v112
	v_fmac_f32_e32 v21, s15, v113
	v_fmac_f32_e32 v22, s15, v114
	v_fmac_f32_e32 v23, s15, v115
	v_fmac_f32_e32 v24, s16, v112
	v_fmac_f32_e32 v25, s16, v113
	v_fmac_f32_e32 v26, s16, v114
	v_fmac_f32_e32 v27, s16, v115
	v_fmac_f32_e32 v28, s17, v112
	v_fmac_f32_e32 v29, s17, v113
	v_fmac_f32_e32 v30, s17, v114
	v_fmac_f32_e32 v31, s17, v115
	v_fmac_f32_e32 v32, s18, v112
	v_fmac_f32_e32 v33, s18, v113
	v_fmac_f32_e32 v34, s18, v114
	v_fmac_f32_e32 v35, s18, v115
	v_readlane_b32 s10, v36, 41
	v_readlane_b32 s11, v37, 41
	v_readlane_b32 s12, v38, 41
	v_readlane_b32 s13, v39, 41
	v_readlane_b32 s14, v40, 41
	v_readlane_b32 s15, v41, 41
	v_readlane_b32 s16, v42, 41
	v_readlane_b32 s17, v43, 41
	v_readlane_b32 s18, v44, 41
	v_fmac_f32_e32 v0, s10, v116
	v_fmac_f32_e32 v1, s10, v117
	v_fmac_f32_e32 v2, s10, v118
	v_fmac_f32_e32 v3, s10, v119
	v_fmac_f32_e32 v4, s11, v116
	v_fmac_f32_e32 v5, s11, v117
	v_fmac_f32_e32 v6, s11, v118
	v_fmac_f32_e32 v7, s11, v119
	v_fmac_f32_e32 v8, s12, v116
	v_fmac_f32_e32 v9, s12, v117
	v_fmac_f32_e32 v10, s12, v118
	v_fmac_f32_e32 v11, s12, v119
	v_fmac_f32_e32 v12, s13, v116
	v_fmac_f32_e32 v13, s13, v117
	v_fmac_f32_e32 v14, s13, v118
	v_fmac_f32_e32 v15, s13, v119
	v_fmac_f32_e32 v16, s14, v116
	v_fmac_f32_e32 v17, s14, v117
	v_fmac_f32_e32 v18, s14, v118
	v_fmac_f32_e32 v19, s14, v119
	v_fmac_f32_e32 v20, s15, v116
	v_fmac_f32_e32 v21, s15, v117
	v_fmac_f32_e32 v22, s15, v118
	v_fmac_f32_e32 v23, s15, v119
; __device__ __forceinline__ void gemv_item(const float* c, const float* c_ctx, const float* ada_w, const float* ada_b, float* mod, int it, int lane) {
;     ...
;     for (int kk = 0; kk < 64; ++kk) { const f32x4 w = *(const f32x4*)(W + (size_t)kk * 6144);
; #pragma unroll
;         for (int r = 0; r < 9; ++r) { const float sk = __uint_as_float(__builtin_amdgcn_readlane(__float_as_uint(s[r]), kk)); acc[r] += w * sk; } }
	v_fmac_f32_e32 v24, s16, v116
	v_fmac_f32_e32 v25, s16, v117
	v_fmac_f32_e32 v26, s16, v118
	v_fmac_f32_e32 v27, s16, v119
	v_fmac_f32_e32 v28, s17, v116
	v_fmac_f32_e32 v29, s17, v117
	v_fmac_f32_e32 v30, s17, v118
	v_fmac_f32_e32 v31, s17, v119
	v_fmac_f32_e32 v32, s18, v116
	v_fmac_f32_e32 v33, s18, v117
	v_fmac_f32_e32 v34, s18, v118
	v_fmac_f32_e32 v35, s18, v119
	v_readlane_b32 s10, v36, 42
	v_readlane_b32 s11, v37, 42
	v_readlane_b32 s12, v38, 42
	v_readlane_b32 s13, v39, 42
	v_readlane_b32 s14, v40, 42
	v_readlane_b32 s15, v41, 42
	v_readlane_b32 s16, v42, 42
	v_readlane_b32 s17, v43, 42
	v_readlane_b32 s18, v44, 42
	v_fmac_f32_e32 v0, s10, v120
	v_fmac_f32_e32 v1, s10, v121
	v_fmac_f32_e32 v2, s10, v122
	v_fmac_f32_e32 v3, s10, v123
	v_fmac_f32_e32 v4, s11, v120
	v_fmac_f32_e32 v5, s11, v121
	v_fmac_f32_e32 v6, s11, v122
	v_fmac_f32_e32 v7, s11, v123
	v_fmac_f32_e32 v8, s12, v120
	v_fmac_f32_e32 v9, s12, v121
	v_fmac_f32_e32 v10, s12, v122
	v_fmac_f32_e32 v11, s12, v123
	v_fmac_f32_e32 v12, s13, v120
	v_fmac_f32_e32 v13, s13, v121
	v_fmac_f32_e32 v14, s13, v122
	v_fmac_f32_e32 v15, s13, v123
	v_fmac_f32_e32 v16, s14, v120
	v_fmac_f32_e32 v17, s14, v121
	v_fmac_f32_e32 v18, s14, v122
	v_fmac_f32_e32 v19, s14, v123
	v_fmac_f32_e32 v20, s15, v120
	v_fmac_f32_e32 v21, s15, v121
	v_fmac_f32_e32 v22, s15, v122
	v_fmac_f32_e32 v23, s15, v123
	v_fmac_f32_e32 v24, s16, v120
	v_fmac_f32_e32 v25, s16, v121
	v_fmac_f32_e32 v26, s16, v122
	v_fmac_f32_e32 v27, s16, v123
	v_fmac_f32_e32 v28, s17, v120
	v_fmac_f32_e32 v29, s17, v121
	v_fmac_f32_e32 v30, s17, v122
	v_fmac_f32_e32 v31, s17, v123
	v_fmac_f32_e32 v32, s18, v120
	v_fmac_f32_e32 v33, s18, v121
	v_fmac_f32_e32 v34, s18, v122
	v_fmac_f32_e32 v35, s18, v123
	v_readlane_b32 s10, v36, 43
	v_readlane_b32 s11, v37, 43
	v_readlane_b32 s12, v38, 43
	v_readlane_b32 s13, v39, 43
	v_readlane_b32 s14, v40, 43
	v_readlane_b32 s15, v41, 43
	v_readlane_b32 s16, v42, 43
	v_readlane_b32 s17, v43, 43
	v_readlane_b32 s18, v44, 43
	v_fmac_f32_e32 v0, s10, v124
	v_fmac_f32_e32 v1, s10, v125
	v_fmac_f32_e32 v2, s10, v126
	v_fmac_f32_e32 v3, s10, v127
	v_fmac_f32_e32 v4, s11, v124
	v_fmac_f32_e32 v5, s11, v125
	v_fmac_f32_e32 v6, s11, v126
	v_fmac_f32_e32 v7, s11, v127
	v_fmac_f32_e32 v8, s12, v124
	v_fmac_f32_e32 v9, s12, v125
	v_fmac_f32_e32 v10, s12, v126
	v_fmac_f32_e32 v11, s12, v127
	v_fmac_f32_e32 v12, s13, v124
	v_fmac_f32_e32 v13, s13, v125
	v_fmac_f32_e32 v14, s13, v126
	v_fmac_f32_e32 v15, s13, v127
	v_fmac_f32_e32 v16, s14, v124
	v_fmac_f32_e32 v17, s14, v125
	v_fmac_f32_e32 v18, s14, v126
	v_fmac_f32_e32 v19, s14, v127
	v_fmac_f32_e32 v20, s15, v124
	v_fmac_f32_e32 v21, s15, v125
	v_fmac_f32_e32 v22, s15, v126
	v_fmac_f32_e32 v23, s15, v127
	v_fmac_f32_e32 v24, s16, v124
	v_fmac_f32_e32 v25, s16, v125
	v_fmac_f32_e32 v26, s16, v126
	v_fmac_f32_e32 v27, s16, v127
	v_fmac_f32_e32 v28, s17, v124
	v_fmac_f32_e32 v29, s17, v125
	v_fmac_f32_e32 v30, s17, v126
	v_fmac_f32_e32 v31, s17, v127
	v_fmac_f32_e32 v32, s18, v124
	v_fmac_f32_e32 v33, s18, v125
	v_fmac_f32_e32 v34, s18, v126
	v_fmac_f32_e32 v35, s18, v127
	v_readlane_b32 s10, v36, 44
	v_readlane_b32 s11, v37, 44
	v_readlane_b32 s12, v38, 44
	v_readlane_b32 s13, v39, 44
	v_readlane_b32 s14, v40, 44
	v_readlane_b32 s15, v41, 44
	v_readlane_b32 s16, v42, 44
	v_readlane_b32 s17, v43, 44
	v_readlane_b32 s18, v44, 44
	v_fmac_f32_e32 v0, s10, v128
	v_fmac_f32_e32 v1, s10, v129
	v_fmac_f32_e32 v2, s10, v130
	v_fmac_f32_e32 v3, s10, v131
	v_fmac_f32_e32 v4, s11, v128
	v_fmac_f32_e32 v5, s11, v129
	v_fmac_f32_e32 v6, s11, v130
	v_fmac_f32_e32 v7, s11, v131
	v_fmac_f32_e32 v8, s12, v128
	v_fmac_f32_e32 v9, s12, v129
	v_fmac_f32_e32 v10, s12, v130
	v_fmac_f32_e32 v11, s12, v131
	v_fmac_f32_e32 v12, s13, v128
	v_fmac_f32_e32 v13, s13, v129
	v_fmac_f32_e32 v14, s13, v130
	v_fmac_f32_e32 v15, s13, v131
	v_fmac_f32_e32 v16, s14, v128
	v_fmac_f32_e32 v17, s14, v129
	v_fmac_f32_e32 v18, s14, v130
	v_fmac_f32_e32 v19, s14, v131
	v_fmac_f32_e32 v20, s15, v128
	v_fmac_f32_e32 v21, s15, v129
	v_fmac_f32_e32 v22, s15, v130
	v_fmac_f32_e32 v23, s15, v131
	v_fmac_f32_e32 v24, s16, v128
	v_fmac_f32_e32 v25, s16, v129
	v_fmac_f32_e32 v26, s16, v130
	v_fmac_f32_e32 v27, s16, v131
	v_fmac_f32_e32 v28, s17, v128
	v_fmac_f32_e32 v29, s17, v129
	v_fmac_f32_e32 v30, s17, v130
	v_fmac_f32_e32 v31, s17, v131
	v_fmac_f32_e32 v32, s18, v128
	v_fmac_f32_e32 v33, s18, v129
	v_fmac_f32_e32 v34, s18, v130
	v_fmac_f32_e32 v35, s18, v131
	v_readlane_b32 s10, v36, 45
	v_readlane_b32 s11, v37, 45
	v_readlane_b32 s12, v38, 45
	v_readlane_b32 s13, v39, 45
	v_readlane_b32 s14, v40, 45
	v_readlane_b32 s15, v41, 45
	v_readlane_b32 s16, v42, 45
	v_readlane_b32 s17, v43, 45
	v_readlane_b32 s18, v44, 45
	v_fmac_f32_e32 v0, s10, v132
	v_fmac_f32_e32 v1, s10, v133
	v_fmac_f32_e32 v2, s10, v134
	v_fmac_f32_e32 v3, s10, v135
	v_fmac_f32_e32 v4, s11, v132
	v_fmac_f32_e32 v5, s11, v133
	v_fmac_f32_e32 v6, s11, v134
	v_fmac_f32_e32 v7, s11, v135
	v_fmac_f32_e32 v8, s12, v132
	v_fmac_f32_e32 v9, s12, v133
	v_fmac_f32_e32 v10, s12, v134
	v_fmac_f32_e32 v11, s12, v135
	v_fmac_f32_e32 v12, s13, v132
	v_fmac_f32_e32 v13, s13, v133
	v_fmac_f32_e32 v14, s13, v134
	v_fmac_f32_e32 v15, s13, v135
	v_fmac_f32_e32 v16, s14, v132
	v_fmac_f32_e32 v17, s14, v133
	v_fmac_f32_e32 v18, s14, v134
	v_fmac_f32_e32 v19, s14, v135
	v_fmac_f32_e32 v20, s15, v132
	v_fmac_f32_e32 v21, s15, v133
	v_fmac_f32_e32 v22, s15, v134
	v_fmac_f32_e32 v23, s15, v135
	v_fmac_f32_e32 v24, s16, v132
	v_fmac_f32_e32 v25, s16, v133
	v_fmac_f32_e32 v26, s16, v134
	v_fmac_f32_e32 v27, s16, v135
	v_fmac_f32_e32 v28, s17, v132
	v_fmac_f32_e32 v29, s17, v133
; __device__ __forceinline__ void gemv_item(const float* c, const float* c_ctx, const float* ada_w, const float* ada_b, float* mod, int it, int lane) {
;     ...
;     for (int kk = 0; kk < 64; ++kk) { const f32x4 w = *(const f32x4*)(W + (size_t)kk * 6144);
; #pragma unroll
;         for (int r = 0; r < 9; ++r) { const float sk = __uint_as_float(__builtin_amdgcn_readlane(__float_as_uint(s[r]), kk)); acc[r] += w * sk; } }
;     const int col = cgp * 256 + lane * 4;
;     f32x4 bv = (f32x4){0.f, 0.f, 0.f, 0.f};
;     if (kc == 0) bv = *(const f32x4*)(ada_b + l * 6144 + col);
; #pragma unroll
;     for (int r = 0; r < 9; ++r) { float* m = mod + (size_t)(l * 9 + r) * 6144 + col;
; #pragma unroll
;         for (int j = 0; j < 4; ++j) atomicAdd(m + j, acc[r][j] + bv[j]); }
	v_fmac_f32_e32 v30, s17, v134
	v_fmac_f32_e32 v31, s17, v135
	v_fmac_f32_e32 v32, s18, v132
	v_fmac_f32_e32 v33, s18, v133
	v_fmac_f32_e32 v34, s18, v134
	v_fmac_f32_e32 v35, s18, v135
	v_readlane_b32 s10, v36, 46
	v_readlane_b32 s11, v37, 46
	v_readlane_b32 s12, v38, 46
	v_readlane_b32 s13, v39, 46
	v_readlane_b32 s14, v40, 46
	v_readlane_b32 s15, v41, 46
	v_readlane_b32 s16, v42, 46
	v_readlane_b32 s17, v43, 46
	v_readlane_b32 s18, v44, 46
	v_fmac_f32_e32 v0, s10, v136
	v_fmac_f32_e32 v1, s10, v137
	v_fmac_f32_e32 v2, s10, v138
	v_fmac_f32_e32 v3, s10, v139
	v_fmac_f32_e32 v4, s11, v136
	v_fmac_f32_e32 v5, s11, v137
	v_fmac_f32_e32 v6, s11, v138
	v_fmac_f32_e32 v7, s11, v139
	v_fmac_f32_e32 v8, s12, v136
	v_fmac_f32_e32 v9, s12, v137
	v_fmac_f32_e32 v10, s12, v138
	v_fmac_f32_e32 v11, s12, v139
	v_fmac_f32_e32 v12, s13, v136
	v_fmac_f32_e32 v13, s13, v137
	v_fmac_f32_e32 v14, s13, v138
	v_fmac_f32_e32 v15, s13, v139
	v_fmac_f32_e32 v16, s14, v136
	v_fmac_f32_e32 v17, s14, v137
	v_fmac_f32_e32 v18, s14, v138
	v_fmac_f32_e32 v19, s14, v139
	v_fmac_f32_e32 v20, s15, v136
	v_fmac_f32_e32 v21, s15, v137
	v_fmac_f32_e32 v22, s15, v138
	v_fmac_f32_e32 v23, s15, v139
	v_fmac_f32_e32 v24, s16, v136
	v_fmac_f32_e32 v25, s16, v137
	v_fmac_f32_e32 v26, s16, v138
	v_fmac_f32_e32 v27, s16, v139
	v_fmac_f32_e32 v28, s17, v136
	v_fmac_f32_e32 v29, s17, v137
	v_fmac_f32_e32 v30, s17, v138
	v_fmac_f32_e32 v31, s17, v139
	v_fmac_f32_e32 v32, s18, v136
	v_fmac_f32_e32 v33, s18, v137
	v_fmac_f32_e32 v34, s18, v138
	v_fmac_f32_e32 v35, s18, v139
	v_readlane_b32 s10, v36, 47
	v_readlane_b32 s11, v37, 47
	v_readlane_b32 s12, v38, 47
	v_readlane_b32 s13, v39, 47
	v_readlane_b32 s14, v40, 47
	v_readlane_b32 s15, v41, 47
	v_readlane_b32 s16, v42, 47
	v_readlane_b32 s17, v43, 47
	v_readlane_b32 s18, v44, 47
	v_fmac_f32_e32 v0, s10, v140
	v_fmac_f32_e32 v1, s10, v141
	v_fmac_f32_e32 v2, s10, v142
	v_fmac_f32_e32 v3, s10, v143
	v_fmac_f32_e32 v4, s11, v140
	v_fmac_f32_e32 v5, s11, v141
	v_fmac_f32_e32 v6, s11, v142
	v_fmac_f32_e32 v7, s11, v143
	v_fmac_f32_e32 v8, s12, v140
	v_fmac_f32_e32 v9, s12, v141
	v_fmac_f32_e32 v10, s12, v142
	v_fmac_f32_e32 v11, s12, v143
	v_fmac_f32_e32 v12, s13, v140
	v_fmac_f32_e32 v13, s13, v141
	v_fmac_f32_e32 v14, s13, v142
	v_fmac_f32_e32 v15, s13, v143
	v_fmac_f32_e32 v16, s14, v140
	v_fmac_f32_e32 v17, s14, v141
	v_fmac_f32_e32 v18, s14, v142
	v_fmac_f32_e32 v19, s14, v143
	v_fmac_f32_e32 v20, s15, v140
	v_fmac_f32_e32 v21, s15, v141
	v_fmac_f32_e32 v22, s15, v142
	v_fmac_f32_e32 v23, s15, v143
	v_fmac_f32_e32 v24, s16, v140
	v_fmac_f32_e32 v25, s16, v141
	v_fmac_f32_e32 v26, s16, v142
	v_fmac_f32_e32 v27, s16, v143
	v_fmac_f32_e32 v28, s17, v140
	v_fmac_f32_e32 v29, s17, v141
	v_fmac_f32_e32 v30, s17, v142
	v_fmac_f32_e32 v31, s17, v143
	v_fmac_f32_e32 v32, s18, v140
	v_fmac_f32_e32 v33, s18, v141
	v_fmac_f32_e32 v34, s18, v142
	v_fmac_f32_e32 v35, s18, v143
	s_waitcnt vmcnt(0)
	v_readlane_b32 s10, v36, 48
	v_readlane_b32 s11, v37, 48
	v_readlane_b32 s12, v38, 48
	v_readlane_b32 s13, v39, 48
	v_readlane_b32 s14, v40, 48
	v_readlane_b32 s15, v41, 48
	v_readlane_b32 s16, v42, 48
	v_readlane_b32 s17, v43, 48
	v_readlane_b32 s18, v44, 48
	v_fmac_f32_e32 v0, s10, v144
	v_fmac_f32_e32 v1, s10, v145
	v_fmac_f32_e32 v2, s10, v146
	v_fmac_f32_e32 v3, s10, v147
	v_fmac_f32_e32 v4, s11, v144
	v_fmac_f32_e32 v5, s11, v145
	v_fmac_f32_e32 v6, s11, v146
	v_fmac_f32_e32 v7, s11, v147
	v_fmac_f32_e32 v8, s12, v144
	v_fmac_f32_e32 v9, s12, v145
	v_fmac_f32_e32 v10, s12, v146
	v_fmac_f32_e32 v11, s12, v147
	v_fmac_f32_e32 v12, s13, v144
	v_fmac_f32_e32 v13, s13, v145
	v_fmac_f32_e32 v14, s13, v146
	v_fmac_f32_e32 v15, s13, v147
	v_fmac_f32_e32 v16, s14, v144
	v_fmac_f32_e32 v17, s14, v145
	v_fmac_f32_e32 v18, s14, v146
	v_fmac_f32_e32 v19, s14, v147
	v_fmac_f32_e32 v20, s15, v144
	v_fmac_f32_e32 v21, s15, v145
	v_fmac_f32_e32 v22, s15, v146
	v_fmac_f32_e32 v23, s15, v147
	v_fmac_f32_e32 v24, s16, v144
	v_fmac_f32_e32 v25, s16, v145
	v_fmac_f32_e32 v26, s16, v146
	v_fmac_f32_e32 v27, s16, v147
	v_fmac_f32_e32 v28, s17, v144
	v_fmac_f32_e32 v29, s17, v145
	v_fmac_f32_e32 v30, s17, v146
	v_fmac_f32_e32 v31, s17, v147
	v_fmac_f32_e32 v32, s18, v144
	v_fmac_f32_e32 v33, s18, v145
	v_fmac_f32_e32 v34, s18, v146
	v_fmac_f32_e32 v35, s18, v147
	v_readlane_b32 s10, v36, 49
	v_readlane_b32 s11, v37, 49
	v_readlane_b32 s12, v38, 49
	v_readlane_b32 s13, v39, 49
	v_readlane_b32 s14, v40, 49
	v_readlane_b32 s15, v41, 49
	v_readlane_b32 s16, v42, 49
	v_readlane_b32 s17, v43, 49
	v_readlane_b32 s18, v44, 49
	v_fmac_f32_e32 v0, s10, v148
	v_fmac_f32_e32 v1, s10, v149
	v_fmac_f32_e32 v2, s10, v150
	v_fmac_f32_e32 v3, s10, v151
	v_fmac_f32_e32 v4, s11, v148
	v_fmac_f32_e32 v5, s11, v149
	v_fmac_f32_e32 v6, s11, v150
	v_fmac_f32_e32 v7, s11, v151
	v_fmac_f32_e32 v8, s12, v148
	v_fmac_f32_e32 v9, s12, v149
	v_fmac_f32_e32 v10, s12, v150
	v_fmac_f32_e32 v11, s12, v151
	v_fmac_f32_e32 v12, s13, v148
	v_fmac_f32_e32 v13, s13, v149
	v_fmac_f32_e32 v14, s13, v150
	v_fmac_f32_e32 v15, s13, v151
	v_fmac_f32_e32 v16, s14, v148
	v_fmac_f32_e32 v17, s14, v149
	v_fmac_f32_e32 v18, s14, v150
	v_fmac_f32_e32 v19, s14, v151
	v_fmac_f32_e32 v20, s15, v148
	v_fmac_f32_e32 v21, s15, v149
	v_fmac_f32_e32 v22, s15, v150
	v_fmac_f32_e32 v23, s15, v151
	v_fmac_f32_e32 v24, s16, v148
	v_fmac_f32_e32 v25, s16, v149
	v_fmac_f32_e32 v26, s16, v150
	v_fmac_f32_e32 v27, s16, v151
	v_fmac_f32_e32 v28, s17, v148
	v_fmac_f32_e32 v29, s17, v149
	v_fmac_f32_e32 v30, s17, v150
	v_fmac_f32_e32 v31, s17, v151
	v_fmac_f32_e32 v32, s18, v148
	v_fmac_f32_e32 v33, s18, v149
	v_fmac_f32_e32 v34, s18, v150
; __device__ __forceinline__ void gemv_item(const float* c, const float* c_ctx, const float* ada_w, const float* ada_b, float* mod, int it, int lane) {
;     ...
;     for (int kk = 0; kk < 64; ++kk) { const f32x4 w = *(const f32x4*)(W + (size_t)kk * 6144);
; #pragma unroll
;         for (int r = 0; r < 9; ++r) { const float sk = __uint_as_float(__builtin_amdgcn_readlane(__float_as_uint(s[r]), kk)); acc[r] += w * sk; } }
	v_fmac_f32_e32 v35, s18, v151
	v_readlane_b32 s10, v36, 50
	v_readlane_b32 s11, v37, 50
	v_readlane_b32 s12, v38, 50
	v_readlane_b32 s13, v39, 50
	v_readlane_b32 s14, v40, 50
	v_readlane_b32 s15, v41, 50
	v_readlane_b32 s16, v42, 50
	v_readlane_b32 s17, v43, 50
	v_readlane_b32 s18, v44, 50
	v_fmac_f32_e32 v0, s10, v152
	v_fmac_f32_e32 v1, s10, v153
	v_fmac_f32_e32 v2, s10, v154
	v_fmac_f32_e32 v3, s10, v155
	v_fmac_f32_e32 v4, s11, v152
	v_fmac_f32_e32 v5, s11, v153
	v_fmac_f32_e32 v6, s11, v154
	v_fmac_f32_e32 v7, s11, v155
	v_fmac_f32_e32 v8, s12, v152
	v_fmac_f32_e32 v9, s12, v153
	v_fmac_f32_e32 v10, s12, v154
	v_fmac_f32_e32 v11, s12, v155
	v_fmac_f32_e32 v12, s13, v152
	v_fmac_f32_e32 v13, s13, v153
	v_fmac_f32_e32 v14, s13, v154
	v_fmac_f32_e32 v15, s13, v155
	v_fmac_f32_e32 v16, s14, v152
	v_fmac_f32_e32 v17, s14, v153
	v_fmac_f32_e32 v18, s14, v154
	v_fmac_f32_e32 v19, s14, v155
	v_fmac_f32_e32 v20, s15, v152
	v_fmac_f32_e32 v21, s15, v153
	v_fmac_f32_e32 v22, s15, v154
	v_fmac_f32_e32 v23, s15, v155
	v_fmac_f32_e32 v24, s16, v152
	v_fmac_f32_e32 v25, s16, v153
	v_fmac_f32_e32 v26, s16, v154
	v_fmac_f32_e32 v27, s16, v155
	v_fmac_f32_e32 v28, s17, v152
	v_fmac_f32_e32 v29, s17, v153
	v_fmac_f32_e32 v30, s17, v154
	v_fmac_f32_e32 v31, s17, v155
	v_fmac_f32_e32 v32, s18, v152
	v_fmac_f32_e32 v33, s18, v153
	v_fmac_f32_e32 v34, s18, v154
	v_fmac_f32_e32 v35, s18, v155
	v_readlane_b32 s10, v36, 51
	v_readlane_b32 s11, v37, 51
	v_readlane_b32 s12, v38, 51
	v_readlane_b32 s13, v39, 51
	v_readlane_b32 s14, v40, 51
	v_readlane_b32 s15, v41, 51
	v_readlane_b32 s16, v42, 51
	v_readlane_b32 s17, v43, 51
	v_readlane_b32 s18, v44, 51
	v_fmac_f32_e32 v0, s10, v156
	v_fmac_f32_e32 v1, s10, v157
	v_fmac_f32_e32 v2, s10, v158
	v_fmac_f32_e32 v3, s10, v159
	v_fmac_f32_e32 v4, s11, v156
	v_fmac_f32_e32 v5, s11, v157
	v_fmac_f32_e32 v6, s11, v158
	v_fmac_f32_e32 v7, s11, v159
	v_fmac_f32_e32 v8, s12, v156
	v_fmac_f32_e32 v9, s12, v157
	v_fmac_f32_e32 v10, s12, v158
	v_fmac_f32_e32 v11, s12, v159
	v_fmac_f32_e32 v12, s13, v156
	v_fmac_f32_e32 v13, s13, v157
	v_fmac_f32_e32 v14, s13, v158
	v_fmac_f32_e32 v15, s13, v159
	v_fmac_f32_e32 v16, s14, v156
	v_fmac_f32_e32 v17, s14, v157
	v_fmac_f32_e32 v18, s14, v158
	v_fmac_f32_e32 v19, s14, v159
	v_fmac_f32_e32 v20, s15, v156
	v_fmac_f32_e32 v21, s15, v157
	v_fmac_f32_e32 v22, s15, v158
	v_fmac_f32_e32 v23, s15, v159
	v_fmac_f32_e32 v24, s16, v156
	v_fmac_f32_e32 v25, s16, v157
	v_fmac_f32_e32 v26, s16, v158
	v_fmac_f32_e32 v27, s16, v159
	v_fmac_f32_e32 v28, s17, v156
	v_fmac_f32_e32 v29, s17, v157
	v_fmac_f32_e32 v30, s17, v158
	v_fmac_f32_e32 v31, s17, v159
	v_fmac_f32_e32 v32, s18, v156
	v_fmac_f32_e32 v33, s18, v157
	v_fmac_f32_e32 v34, s18, v158
	v_fmac_f32_e32 v35, s18, v159
	v_readlane_b32 s10, v36, 52
	v_readlane_b32 s11, v37, 52
	v_readlane_b32 s12, v38, 52
	v_readlane_b32 s13, v39, 52
	v_readlane_b32 s14, v40, 52
	v_readlane_b32 s15, v41, 52
	v_readlane_b32 s16, v42, 52
	v_readlane_b32 s17, v43, 52
	v_readlane_b32 s18, v44, 52
	v_fmac_f32_e32 v0, s10, v160
	v_fmac_f32_e32 v1, s10, v161
	v_fmac_f32_e32 v2, s10, v162
	v_fmac_f32_e32 v3, s10, v163
	v_fmac_f32_e32 v4, s11, v160
	v_fmac_f32_e32 v5, s11, v161
	v_fmac_f32_e32 v6, s11, v162
	v_fmac_f32_e32 v7, s11, v163
	v_fmac_f32_e32 v8, s12, v160
	v_fmac_f32_e32 v9, s12, v161
	v_fmac_f32_e32 v10, s12, v162
	v_fmac_f32_e32 v11, s12, v163
	v_fmac_f32_e32 v12, s13, v160
	v_fmac_f32_e32 v13, s13, v161
	v_fmac_f32_e32 v14, s13, v162
	v_fmac_f32_e32 v15, s13, v163
	v_fmac_f32_e32 v16, s14, v160
	v_fmac_f32_e32 v17, s14, v161
	v_fmac_f32_e32 v18, s14, v162
	v_fmac_f32_e32 v19, s14, v163
	v_fmac_f32_e32 v20, s15, v160
	v_fmac_f32_e32 v21, s15, v161
	v_fmac_f32_e32 v22, s15, v162
	v_fmac_f32_e32 v23, s15, v163
	v_fmac_f32_e32 v24, s16, v160
	v_fmac_f32_e32 v25, s16, v161
	v_fmac_f32_e32 v26, s16, v162
	v_fmac_f32_e32 v27, s16, v163
	v_fmac_f32_e32 v28, s17, v160
	v_fmac_f32_e32 v29, s17, v161
	v_fmac_f32_e32 v30, s17, v162
	v_fmac_f32_e32 v31, s17, v163
	v_fmac_f32_e32 v32, s18, v160
	v_fmac_f32_e32 v33, s18, v161
	v_fmac_f32_e32 v34, s18, v162
	v_fmac_f32_e32 v35, s18, v163
	v_readlane_b32 s10, v36, 53
	v_readlane_b32 s11, v37, 53
	v_readlane_b32 s12, v38, 53
	v_readlane_b32 s13, v39, 53
	v_readlane_b32 s14, v40, 53
	v_readlane_b32 s15, v41, 53
	v_readlane_b32 s16, v42, 53
	v_readlane_b32 s17, v43, 53
	v_readlane_b32 s18, v44, 53
	v_fmac_f32_e32 v0, s10, v164
	v_fmac_f32_e32 v1, s10, v165
	v_fmac_f32_e32 v2, s10, v166
	v_fmac_f32_e32 v3, s10, v167
	v_fmac_f32_e32 v4, s11, v164
	v_fmac_f32_e32 v5, s11, v165
	v_fmac_f32_e32 v6, s11, v166
	v_fmac_f32_e32 v7, s11, v167
	v_fmac_f32_e32 v8, s12, v164
	v_fmac_f32_e32 v9, s12, v165
	v_fmac_f32_e32 v10, s12, v166
	v_fmac_f32_e32 v11, s12, v167
	v_fmac_f32_e32 v12, s13, v164
	v_fmac_f32_e32 v13, s13, v165
	v_fmac_f32_e32 v14, s13, v166
	v_fmac_f32_e32 v15, s13, v167
	v_fmac_f32_e32 v16, s14, v164
	v_fmac_f32_e32 v17, s14, v165
	v_fmac_f32_e32 v18, s14, v166
	v_fmac_f32_e32 v19, s14, v167
	v_fmac_f32_e32 v20, s15, v164
	v_fmac_f32_e32 v21, s15, v165
	v_fmac_f32_e32 v22, s15, v166
	v_fmac_f32_e32 v23, s15, v167
	v_fmac_f32_e32 v24, s16, v164
	v_fmac_f32_e32 v25, s16, v165
	v_fmac_f32_e32 v26, s16, v166
	v_fmac_f32_e32 v27, s16, v167
	v_fmac_f32_e32 v28, s17, v164
	v_fmac_f32_e32 v29, s17, v165
	v_fmac_f32_e32 v30, s17, v166
	v_fmac_f32_e32 v31, s17, v167
	v_fmac_f32_e32 v32, s18, v164
	v_fmac_f32_e32 v33, s18, v165
	v_fmac_f32_e32 v34, s18, v166
	v_fmac_f32_e32 v35, s18, v167
	v_readlane_b32 s10, v36, 54
	v_readlane_b32 s11, v37, 54
	v_readlane_b32 s12, v38, 54
	v_readlane_b32 s13, v39, 54
	v_readlane_b32 s14, v40, 54
; __device__ __forceinline__ void gemv_item(const float* c, const float* c_ctx, const float* ada_w, const float* ada_b, float* mod, int it, int lane) {
;     ...
;     for (int kk = 0; kk < 64; ++kk) { const f32x4 w = *(const f32x4*)(W + (size_t)kk * 6144);
; #pragma unroll
;         for (int r = 0; r < 9; ++r) { const float sk = __uint_as_float(__builtin_amdgcn_readlane(__float_as_uint(s[r]), kk)); acc[r] += w * sk; } }
	v_readlane_b32 s15, v41, 54
	v_readlane_b32 s16, v42, 54
	v_readlane_b32 s17, v43, 54
	v_readlane_b32 s18, v44, 54
	v_fmac_f32_e32 v0, s10, v168
	v_fmac_f32_e32 v1, s10, v169
	v_fmac_f32_e32 v2, s10, v170
	v_fmac_f32_e32 v3, s10, v171
	v_fmac_f32_e32 v4, s11, v168
	v_fmac_f32_e32 v5, s11, v169
	v_fmac_f32_e32 v6, s11, v170
	v_fmac_f32_e32 v7, s11, v171
	v_fmac_f32_e32 v8, s12, v168
	v_fmac_f32_e32 v9, s12, v169
	v_fmac_f32_e32 v10, s12, v170
	v_fmac_f32_e32 v11, s12, v171
	v_fmac_f32_e32 v12, s13, v168
	v_fmac_f32_e32 v13, s13, v169
	v_fmac_f32_e32 v14, s13, v170
	v_fmac_f32_e32 v15, s13, v171
	v_fmac_f32_e32 v16, s14, v168
	v_fmac_f32_e32 v17, s14, v169
	v_fmac_f32_e32 v18, s14, v170
	v_fmac_f32_e32 v19, s14, v171
	v_fmac_f32_e32 v20, s15, v168
	v_fmac_f32_e32 v21, s15, v169
	v_fmac_f32_e32 v22, s15, v170
	v_fmac_f32_e32 v23, s15, v171
	v_fmac_f32_e32 v24, s16, v168
	v_fmac_f32_e32 v25, s16, v169
	v_fmac_f32_e32 v26, s16, v170
	v_fmac_f32_e32 v27, s16, v171
	v_fmac_f32_e32 v28, s17, v168
	v_fmac_f32_e32 v29, s17, v169
	v_fmac_f32_e32 v30, s17, v170
	v_fmac_f32_e32 v31, s17, v171
	v_fmac_f32_e32 v32, s18, v168
	v_fmac_f32_e32 v33, s18, v169
	v_fmac_f32_e32 v34, s18, v170
	v_fmac_f32_e32 v35, s18, v171
	v_readlane_b32 s10, v36, 55
	v_readlane_b32 s11, v37, 55
	v_readlane_b32 s12, v38, 55
	v_readlane_b32 s13, v39, 55
	v_readlane_b32 s14, v40, 55
	v_readlane_b32 s15, v41, 55
	v_readlane_b32 s16, v42, 55
	v_readlane_b32 s17, v43, 55
	v_readlane_b32 s18, v44, 55
	v_fmac_f32_e32 v0, s10, v172
	v_fmac_f32_e32 v1, s10, v173
	v_fmac_f32_e32 v2, s10, v174
	v_fmac_f32_e32 v3, s10, v175
	v_fmac_f32_e32 v4, s11, v172
	v_fmac_f32_e32 v5, s11, v173
	v_fmac_f32_e32 v6, s11, v174
	v_fmac_f32_e32 v7, s11, v175
	v_fmac_f32_e32 v8, s12, v172
	v_fmac_f32_e32 v9, s12, v173
	v_fmac_f32_e32 v10, s12, v174
	v_fmac_f32_e32 v11, s12, v175
	v_fmac_f32_e32 v12, s13, v172
	v_fmac_f32_e32 v13, s13, v173
	v_fmac_f32_e32 v14, s13, v174
	v_fmac_f32_e32 v15, s13, v175
	v_fmac_f32_e32 v16, s14, v172
	v_fmac_f32_e32 v17, s14, v173
	v_fmac_f32_e32 v18, s14, v174
	v_fmac_f32_e32 v19, s14, v175
	v_fmac_f32_e32 v20, s15, v172
	v_fmac_f32_e32 v21, s15, v173
	v_fmac_f32_e32 v22, s15, v174
	v_fmac_f32_e32 v23, s15, v175
	v_fmac_f32_e32 v24, s16, v172
	v_fmac_f32_e32 v25, s16, v173
	v_fmac_f32_e32 v26, s16, v174
	v_fmac_f32_e32 v27, s16, v175
	v_fmac_f32_e32 v28, s17, v172
	v_fmac_f32_e32 v29, s17, v173
	v_fmac_f32_e32 v30, s17, v174
	v_fmac_f32_e32 v31, s17, v175
	v_fmac_f32_e32 v32, s18, v172
	v_fmac_f32_e32 v33, s18, v173
	v_fmac_f32_e32 v34, s18, v174
	v_fmac_f32_e32 v35, s18, v175
	v_readlane_b32 s10, v36, 56
	v_readlane_b32 s11, v37, 56
	v_readlane_b32 s12, v38, 56
	v_readlane_b32 s13, v39, 56
	v_readlane_b32 s14, v40, 56
	v_readlane_b32 s15, v41, 56
	v_readlane_b32 s16, v42, 56
	v_readlane_b32 s17, v43, 56
	v_readlane_b32 s18, v44, 56
	v_fmac_f32_e32 v0, s10, v176
	v_fmac_f32_e32 v1, s10, v177
	v_fmac_f32_e32 v2, s10, v178
	v_fmac_f32_e32 v3, s10, v179
	v_fmac_f32_e32 v4, s11, v176
	v_fmac_f32_e32 v5, s11, v177
	v_fmac_f32_e32 v6, s11, v178
	v_fmac_f32_e32 v7, s11, v179
	v_fmac_f32_e32 v8, s12, v176
	v_fmac_f32_e32 v9, s12, v177
	v_fmac_f32_e32 v10, s12, v178
	v_fmac_f32_e32 v11, s12, v179
	v_fmac_f32_e32 v12, s13, v176
	v_fmac_f32_e32 v13, s13, v177
	v_fmac_f32_e32 v14, s13, v178
	v_fmac_f32_e32 v15, s13, v179
	v_fmac_f32_e32 v16, s14, v176
	v_fmac_f32_e32 v17, s14, v177
	v_fmac_f32_e32 v18, s14, v178
	v_fmac_f32_e32 v19, s14, v179
	v_fmac_f32_e32 v20, s15, v176
	v_fmac_f32_e32 v21, s15, v177
	v_fmac_f32_e32 v22, s15, v178
	v_fmac_f32_e32 v23, s15, v179
	v_fmac_f32_e32 v24, s16, v176
	v_fmac_f32_e32 v25, s16, v177
	v_fmac_f32_e32 v26, s16, v178
	v_fmac_f32_e32 v27, s16, v179
	v_fmac_f32_e32 v28, s17, v176
	v_fmac_f32_e32 v29, s17, v177
	v_fmac_f32_e32 v30, s17, v178
	v_fmac_f32_e32 v31, s17, v179
	v_fmac_f32_e32 v32, s18, v176
	v_fmac_f32_e32 v33, s18, v177
	v_fmac_f32_e32 v34, s18, v178
	v_fmac_f32_e32 v35, s18, v179
	v_readlane_b32 s10, v36, 57
	v_readlane_b32 s11, v37, 57
	v_readlane_b32 s12, v38, 57
	v_readlane_b32 s13, v39, 57
	v_readlane_b32 s14, v40, 57
	v_readlane_b32 s15, v41, 57
	v_readlane_b32 s16, v42, 57
	v_readlane_b32 s17, v43, 57
	v_readlane_b32 s18, v44, 57
	v_fmac_f32_e32 v0, s10, v180
	v_fmac_f32_e32 v1, s10, v181
	v_fmac_f32_e32 v2, s10, v182
	v_fmac_f32_e32 v3, s10, v183
	v_fmac_f32_e32 v4, s11, v180
	v_fmac_f32_e32 v5, s11, v181
	v_fmac_f32_e32 v6, s11, v182
	v_fmac_f32_e32 v7, s11, v183
	v_fmac_f32_e32 v8, s12, v180
	v_fmac_f32_e32 v9, s12, v181
	v_fmac_f32_e32 v10, s12, v182
	v_fmac_f32_e32 v11, s12, v183
	v_fmac_f32_e32 v12, s13, v180
	v_fmac_f32_e32 v13, s13, v181
	v_fmac_f32_e32 v14, s13, v182
	v_fmac_f32_e32 v15, s13, v183
	v_fmac_f32_e32 v16, s14, v180
	v_fmac_f32_e32 v17, s14, v181
	v_fmac_f32_e32 v18, s14, v182
	v_fmac_f32_e32 v19, s14, v183
	v_fmac_f32_e32 v20, s15, v180
	v_fmac_f32_e32 v21, s15, v181
	v_fmac_f32_e32 v22, s15, v182
	v_fmac_f32_e32 v23, s15, v183
	v_fmac_f32_e32 v24, s16, v180
	v_fmac_f32_e32 v25, s16, v181
	v_fmac_f32_e32 v26, s16, v182
	v_fmac_f32_e32 v27, s16, v183
	v_fmac_f32_e32 v28, s17, v180
	v_fmac_f32_e32 v29, s17, v181
	v_fmac_f32_e32 v30, s17, v182
	v_fmac_f32_e32 v31, s17, v183
	v_fmac_f32_e32 v32, s18, v180
	v_fmac_f32_e32 v33, s18, v181
	v_fmac_f32_e32 v34, s18, v182
	v_fmac_f32_e32 v35, s18, v183
	v_readlane_b32 s10, v36, 58
	v_readlane_b32 s11, v37, 58
	v_readlane_b32 s12, v38, 58
	v_readlane_b32 s13, v39, 58
	v_readlane_b32 s14, v40, 58
	v_readlane_b32 s15, v41, 58
	v_readlane_b32 s16, v42, 58
	v_readlane_b32 s17, v43, 58
	v_readlane_b32 s18, v44, 58
	v_fmac_f32_e32 v0, s10, v184
	v_fmac_f32_e32 v1, s10, v185
; __device__ __forceinline__ void gemv_item(const float* c, const float* c_ctx, const float* ada_w, const float* ada_b, float* mod, int it, int lane) {
;     ...
;     for (int kk = 0; kk < 64; ++kk) { const f32x4 w = *(const f32x4*)(W + (size_t)kk * 6144);
; #pragma unroll
;         for (int r = 0; r < 9; ++r) { const float sk = __uint_as_float(__builtin_amdgcn_readlane(__float_as_uint(s[r]), kk)); acc[r] += w * sk; } }
	v_fmac_f32_e32 v2, s10, v186
	v_fmac_f32_e32 v3, s10, v187
	v_fmac_f32_e32 v4, s11, v184
	v_fmac_f32_e32 v5, s11, v185
	v_fmac_f32_e32 v6, s11, v186
	v_fmac_f32_e32 v7, s11, v187
	v_fmac_f32_e32 v8, s12, v184
	v_fmac_f32_e32 v9, s12, v185
	v_fmac_f32_e32 v10, s12, v186
	v_fmac_f32_e32 v11, s12, v187
	v_fmac_f32_e32 v12, s13, v184
	v_fmac_f32_e32 v13, s13, v185
	v_fmac_f32_e32 v14, s13, v186
	v_fmac_f32_e32 v15, s13, v187
	v_fmac_f32_e32 v16, s14, v184
	v_fmac_f32_e32 v17, s14, v185
	v_fmac_f32_e32 v18, s14, v186
	v_fmac_f32_e32 v19, s14, v187
	v_fmac_f32_e32 v20, s15, v184
	v_fmac_f32_e32 v21, s15, v185
	v_fmac_f32_e32 v22, s15, v186
	v_fmac_f32_e32 v23, s15, v187
	v_fmac_f32_e32 v24, s16, v184
	v_fmac_f32_e32 v25, s16, v185
	v_fmac_f32_e32 v26, s16, v186
	v_fmac_f32_e32 v27, s16, v187
	v_fmac_f32_e32 v28, s17, v184
	v_fmac_f32_e32 v29, s17, v185
	v_fmac_f32_e32 v30, s17, v186
	v_fmac_f32_e32 v31, s17, v187
	v_fmac_f32_e32 v32, s18, v184
	v_fmac_f32_e32 v33, s18, v185
	v_fmac_f32_e32 v34, s18, v186
	v_fmac_f32_e32 v35, s18, v187
	v_readlane_b32 s10, v36, 59
	v_readlane_b32 s11, v37, 59
	v_readlane_b32 s12, v38, 59
	v_readlane_b32 s13, v39, 59
	v_readlane_b32 s14, v40, 59
	v_readlane_b32 s15, v41, 59
	v_readlane_b32 s16, v42, 59
	v_readlane_b32 s17, v43, 59
	v_readlane_b32 s18, v44, 59
	v_fmac_f32_e32 v0, s10, v188
	v_fmac_f32_e32 v1, s10, v189
	v_fmac_f32_e32 v2, s10, v190
	v_fmac_f32_e32 v3, s10, v191
	v_fmac_f32_e32 v4, s11, v188
	v_fmac_f32_e32 v5, s11, v189
	v_fmac_f32_e32 v6, s11, v190
	v_fmac_f32_e32 v7, s11, v191
	v_fmac_f32_e32 v8, s12, v188
	v_fmac_f32_e32 v9, s12, v189
	v_fmac_f32_e32 v10, s12, v190
	v_fmac_f32_e32 v11, s12, v191
	v_fmac_f32_e32 v12, s13, v188
	v_fmac_f32_e32 v13, s13, v189
	v_fmac_f32_e32 v14, s13, v190
	v_fmac_f32_e32 v15, s13, v191
	v_fmac_f32_e32 v16, s14, v188
	v_fmac_f32_e32 v17, s14, v189
	v_fmac_f32_e32 v18, s14, v190
	v_fmac_f32_e32 v19, s14, v191
	v_fmac_f32_e32 v20, s15, v188
	v_fmac_f32_e32 v21, s15, v189
	v_fmac_f32_e32 v22, s15, v190
	v_fmac_f32_e32 v23, s15, v191
	v_fmac_f32_e32 v24, s16, v188
	v_fmac_f32_e32 v25, s16, v189
	v_fmac_f32_e32 v26, s16, v190
	v_fmac_f32_e32 v27, s16, v191
	v_fmac_f32_e32 v28, s17, v188
	v_fmac_f32_e32 v29, s17, v189
	v_fmac_f32_e32 v30, s17, v190
	v_fmac_f32_e32 v31, s17, v191
	v_fmac_f32_e32 v32, s18, v188
	v_fmac_f32_e32 v33, s18, v189
	v_fmac_f32_e32 v34, s18, v190
	v_fmac_f32_e32 v35, s18, v191
	v_readlane_b32 s10, v36, 60
	v_readlane_b32 s11, v37, 60
	v_readlane_b32 s12, v38, 60
	v_readlane_b32 s13, v39, 60
	v_readlane_b32 s14, v40, 60
	v_readlane_b32 s15, v41, 60
	v_readlane_b32 s16, v42, 60
	v_readlane_b32 s17, v43, 60
	v_readlane_b32 s18, v44, 60
	v_fmac_f32_e32 v0, s10, v192
	v_fmac_f32_e32 v1, s10, v193
	v_fmac_f32_e32 v2, s10, v194
	v_fmac_f32_e32 v3, s10, v195
	v_fmac_f32_e32 v4, s11, v192
	v_fmac_f32_e32 v5, s11, v193
	v_fmac_f32_e32 v6, s11, v194
	v_fmac_f32_e32 v7, s11, v195
	v_fmac_f32_e32 v8, s12, v192
	v_fmac_f32_e32 v9, s12, v193
	v_fmac_f32_e32 v10, s12, v194
	v_fmac_f32_e32 v11, s12, v195
	v_fmac_f32_e32 v12, s13, v192
	v_fmac_f32_e32 v13, s13, v193
	v_fmac_f32_e32 v14, s13, v194
	v_fmac_f32_e32 v15, s13, v195
	v_fmac_f32_e32 v16, s14, v192
	v_fmac_f32_e32 v17, s14, v193
	v_fmac_f32_e32 v18, s14, v194
	v_fmac_f32_e32 v19, s14, v195
	v_fmac_f32_e32 v20, s15, v192
	v_fmac_f32_e32 v21, s15, v193
	v_fmac_f32_e32 v22, s15, v194
	v_fmac_f32_e32 v23, s15, v195
	v_fmac_f32_e32 v24, s16, v192
	v_fmac_f32_e32 v25, s16, v193
	v_fmac_f32_e32 v26, s16, v194
	v_fmac_f32_e32 v27, s16, v195
	v_fmac_f32_e32 v28, s17, v192
	v_fmac_f32_e32 v29, s17, v193
	v_fmac_f32_e32 v30, s17, v194
	v_fmac_f32_e32 v31, s17, v195
	v_fmac_f32_e32 v32, s18, v192
	v_fmac_f32_e32 v33, s18, v193
	v_fmac_f32_e32 v34, s18, v194
	v_fmac_f32_e32 v35, s18, v195
	v_readlane_b32 s10, v36, 61
	v_readlane_b32 s11, v37, 61
	v_readlane_b32 s12, v38, 61
	v_readlane_b32 s13, v39, 61
	v_readlane_b32 s14, v40, 61
	v_readlane_b32 s15, v41, 61
	v_readlane_b32 s16, v42, 61
	v_readlane_b32 s17, v43, 61
	v_readlane_b32 s18, v44, 61
	v_fmac_f32_e32 v0, s10, v200
	v_fmac_f32_e32 v1, s10, v201
	v_fmac_f32_e32 v2, s10, v202
	v_fmac_f32_e32 v3, s10, v203
	v_fmac_f32_e32 v4, s11, v200
	v_fmac_f32_e32 v5, s11, v201
	v_fmac_f32_e32 v6, s11, v202
	v_fmac_f32_e32 v7, s11, v203
	v_fmac_f32_e32 v8, s12, v200
	v_fmac_f32_e32 v9, s12, v201
	v_fmac_f32_e32 v10, s12, v202
	v_fmac_f32_e32 v11, s12, v203
	v_fmac_f32_e32 v12, s13, v200
	v_fmac_f32_e32 v13, s13, v201
	v_fmac_f32_e32 v14, s13, v202
	v_fmac_f32_e32 v15, s13, v203
	v_fmac_f32_e32 v16, s14, v200
	v_fmac_f32_e32 v17, s14, v201
	v_fmac_f32_e32 v18, s14, v202
	v_fmac_f32_e32 v19, s14, v203
	v_fmac_f32_e32 v20, s15, v200
	v_fmac_f32_e32 v21, s15, v201
	v_fmac_f32_e32 v22, s15, v202
	v_fmac_f32_e32 v23, s15, v203
	v_fmac_f32_e32 v24, s16, v200
	v_fmac_f32_e32 v25, s16, v201
	v_fmac_f32_e32 v26, s16, v202
	v_fmac_f32_e32 v27, s16, v203
	v_fmac_f32_e32 v28, s17, v200
	v_fmac_f32_e32 v29, s17, v201
	v_fmac_f32_e32 v30, s17, v202
	v_fmac_f32_e32 v31, s17, v203
	v_fmac_f32_e32 v32, s18, v200
	v_fmac_f32_e32 v33, s18, v201
	v_fmac_f32_e32 v34, s18, v202
	v_fmac_f32_e32 v35, s18, v203
	v_readlane_b32 s10, v36, 62
	v_readlane_b32 s11, v37, 62
	v_readlane_b32 s12, v38, 62
	v_readlane_b32 s13, v39, 62
	v_readlane_b32 s14, v40, 62
	v_readlane_b32 s15, v41, 62
	v_readlane_b32 s16, v42, 62
	v_readlane_b32 s17, v43, 62
	v_readlane_b32 s18, v44, 62
	v_fmac_f32_e32 v0, s10, v204
	v_fmac_f32_e32 v1, s10, v205
	v_fmac_f32_e32 v2, s10, v206
	v_fmac_f32_e32 v3, s10, v207
	v_fmac_f32_e32 v4, s11, v204
	v_fmac_f32_e32 v5, s11, v205
	v_fmac_f32_e32 v6, s11, v206
	v_fmac_f32_e32 v7, s11, v207
; __device__ __forceinline__ void gemv_item(const float* c, const float* c_ctx, const float* ada_w, const float* ada_b, float* mod, int it, int lane) {
;     ...
;         for (int r = 0; r < 9; ++r) { const float sk = __uint_as_float(__builtin_amdgcn_readlane(__float_as_uint(s[r]), kk)); acc[r] += w * sk; } }
;     const int col = cgp * 256 + lane * 4;
;     f32x4 bv = (f32x4){0.f, 0.f, 0.f, 0.f};
;     if (kc == 0) bv = *(const f32x4*)(ada_b + l * 6144 + col);
; #pragma unroll
;     for (int r = 0; r < 9; ++r) { float* m = mod + (size_t)(l * 9 + r) * 6144 + col;
; #pragma unroll
;         for (int j = 0; j < 4; ++j) atomicAdd(m + j, acc[r][j] + bv[j]); }
	v_fmac_f32_e32 v8, s12, v204
	v_fmac_f32_e32 v9, s12, v205
	v_fmac_f32_e32 v10, s12, v206
	v_fmac_f32_e32 v11, s12, v207
	v_fmac_f32_e32 v12, s13, v204
	v_fmac_f32_e32 v13, s13, v205
	v_fmac_f32_e32 v14, s13, v206
	v_fmac_f32_e32 v15, s13, v207
	v_fmac_f32_e32 v16, s14, v204
	v_fmac_f32_e32 v17, s14, v205
	v_fmac_f32_e32 v18, s14, v206
	v_fmac_f32_e32 v19, s14, v207
	v_fmac_f32_e32 v20, s15, v204
	v_fmac_f32_e32 v21, s15, v205
	v_fmac_f32_e32 v22, s15, v206
	v_fmac_f32_e32 v23, s15, v207
	v_fmac_f32_e32 v24, s16, v204
	v_fmac_f32_e32 v25, s16, v205
	v_fmac_f32_e32 v26, s16, v206
	v_fmac_f32_e32 v27, s16, v207
	v_fmac_f32_e32 v28, s17, v204
	v_fmac_f32_e32 v29, s17, v205
	v_fmac_f32_e32 v30, s17, v206
	v_fmac_f32_e32 v31, s17, v207
	v_fmac_f32_e32 v32, s18, v204
	v_fmac_f32_e32 v33, s18, v205
	v_fmac_f32_e32 v34, s18, v206
	v_fmac_f32_e32 v35, s18, v207
	v_readlane_b32 s10, v36, 63
	v_readlane_b32 s11, v37, 63
	v_readlane_b32 s12, v38, 63
	v_readlane_b32 s13, v39, 63
	v_readlane_b32 s14, v40, 63
	v_readlane_b32 s15, v41, 63
	v_readlane_b32 s16, v42, 63
	v_readlane_b32 s17, v43, 63
	v_readlane_b32 s18, v44, 63
	v_fmac_f32_e32 v0, s10, v208
	v_fmac_f32_e32 v1, s10, v209
	v_fmac_f32_e32 v2, s10, v210
	v_fmac_f32_e32 v3, s10, v211
	v_fmac_f32_e32 v4, s11, v208
	v_fmac_f32_e32 v5, s11, v209
	v_fmac_f32_e32 v6, s11, v210
	v_fmac_f32_e32 v7, s11, v211
	v_fmac_f32_e32 v8, s12, v208
	v_fmac_f32_e32 v9, s12, v209
	v_fmac_f32_e32 v10, s12, v210
	v_fmac_f32_e32 v11, s12, v211
	v_fmac_f32_e32 v12, s13, v208
	v_fmac_f32_e32 v13, s13, v209
	v_fmac_f32_e32 v14, s13, v210
	v_fmac_f32_e32 v15, s13, v211
	v_fmac_f32_e32 v16, s14, v208
	v_fmac_f32_e32 v17, s14, v209
	v_fmac_f32_e32 v18, s14, v210
	v_fmac_f32_e32 v19, s14, v211
	v_fmac_f32_e32 v20, s15, v208
	v_fmac_f32_e32 v21, s15, v209
	v_fmac_f32_e32 v22, s15, v210
	v_fmac_f32_e32 v23, s15, v211
	v_fmac_f32_e32 v24, s16, v208
	v_fmac_f32_e32 v25, s16, v209
	v_fmac_f32_e32 v26, s16, v210
	v_fmac_f32_e32 v27, s16, v211
	v_fmac_f32_e32 v28, s17, v208
	v_fmac_f32_e32 v29, s17, v209
	v_fmac_f32_e32 v30, s17, v210
	v_fmac_f32_e32 v31, s17, v211
	v_fmac_f32_e32 v32, s18, v208
	v_fmac_f32_e32 v33, s18, v209
	v_fmac_f32_e32 v34, s18, v210
	v_fmac_f32_e32 v35, s18, v211
	v_add_f32_e32 v0, v0, v52
	v_add_f32_e32 v1, v1, v53
	v_add_f32_e32 v2, v2, v54
	v_add_f32_e32 v3, v3, v55
	v_add_f32_e32 v4, v4, v52
	v_add_f32_e32 v5, v5, v53
	v_add_f32_e32 v6, v6, v54
	v_add_f32_e32 v7, v7, v55
	v_add_f32_e32 v8, v8, v52
	v_add_f32_e32 v9, v9, v53
	v_add_f32_e32 v10, v10, v54
	v_add_f32_e32 v11, v11, v55
	v_add_f32_e32 v12, v12, v52
	v_add_f32_e32 v13, v13, v53
	v_add_f32_e32 v14, v14, v54
	v_add_f32_e32 v15, v15, v55
	v_add_f32_e32 v16, v16, v52
	v_add_f32_e32 v17, v17, v53
	v_add_f32_e32 v18, v18, v54
	v_add_f32_e32 v19, v19, v55
	v_add_f32_e32 v20, v20, v52
	v_add_f32_e32 v21, v21, v53
	v_add_f32_e32 v22, v22, v54
	v_add_f32_e32 v23, v23, v55
	v_add_f32_e32 v24, v24, v52
	v_add_f32_e32 v25, v25, v53
	v_add_f32_e32 v26, v26, v54
	v_add_f32_e32 v27, v27, v55
	v_add_f32_e32 v28, v28, v52
	v_add_f32_e32 v29, v29, v53
	v_add_f32_e32 v30, v30, v54
	v_add_f32_e32 v31, v31, v55
	v_add_f32_e32 v32, v32, v52
	v_add_f32_e32 v33, v33, v53
	v_add_f32_e32 v34, v34, v54
	v_add_f32_e32 v35, v35, v55
	v_add_u32_e32 v47, s31, v46
	v_add_u32_e32 v48, s31, v45
	ds_write_b128 v47, v[0:3] offset:0
	ds_write_b128 v47, v[4:7] offset:1024
	ds_write_b128 v47, v[8:11] offset:2048
	ds_write_b128 v47, v[12:15] offset:3072
	ds_write_b128 v47, v[16:19] offset:4096
	ds_write_b128 v47, v[20:23] offset:5120
	ds_write_b128 v47, v[24:27] offset:6144
	ds_write_b128 v47, v[28:31] offset:7168
	ds_write_b128 v47, v[32:35] offset:8192
	s_waitcnt lgkmcnt(0)
; __device__ __forceinline__ void gemv_item(const float* c, const float* c_ctx, const float* ada_w, const float* ada_b, float* mod, int it, int lane) {
;     ...
; #pragma unroll
;     for (int r = 0; r < 9; ++r) { float* m = mod + (size_t)(l * 9 + r) * 6144 + col;
; #pragma unroll
;         for (int j = 0; j < 4; ++j) atomicAdd(m + j, acc[r][j] + bv[j]); }
	ds_read_b32 v80, v48 offset:0
	ds_read_b32 v81, v48 offset:256
	ds_read_b32 v82, v48 offset:512
	ds_read_b32 v83, v48 offset:768
	ds_read_b32 v84, v48 offset:1024
	ds_read_b32 v85, v48 offset:1280
	ds_read_b32 v86, v48 offset:1536
	ds_read_b32 v87, v48 offset:1792
	ds_read_b32 v88, v48 offset:2048
	ds_read_b32 v89, v48 offset:2304
	ds_read_b32 v90, v48 offset:2560
	ds_read_b32 v91, v48 offset:2816
	ds_read_b32 v92, v48 offset:3072
	ds_read_b32 v93, v48 offset:3328
	ds_read_b32 v94, v48 offset:3584
	ds_read_b32 v95, v48 offset:3840
	ds_read_b32 v96, v48 offset:4096
	ds_read_b32 v97, v48 offset:4352
	ds_read_b32 v98, v48 offset:4608
	ds_read_b32 v99, v48 offset:4864
	ds_read_b32 v100, v48 offset:5120
	ds_read_b32 v101, v48 offset:5376
	ds_read_b32 v102, v48 offset:5632
	ds_read_b32 v103, v48 offset:5888
	ds_read_b32 v104, v48 offset:6144
	ds_read_b32 v105, v48 offset:6400
	ds_read_b32 v106, v48 offset:6656
	ds_read_b32 v107, v48 offset:6912
	ds_read_b32 v108, v48 offset:7168
	ds_read_b32 v109, v48 offset:7424
	ds_read_b32 v110, v48 offset:7680
	ds_read_b32 v111, v48 offset:7936
	ds_read_b32 v112, v48 offset:8192
	ds_read_b32 v113, v48 offset:8448
	ds_read_b32 v114, v48 offset:8704
	ds_read_b32 v115, v48 offset:8960
	s_lshl_b32 s5, s4, 10
	s_add_u32 s20, s84, s5
	s_addc_u32 s21, s85, 0
	s_waitcnt lgkmcnt(0)
	global_atomic_add_f32 v45, v80, s[20:21] offset:0
	global_atomic_add_f32 v45, v81, s[20:21] offset:256
	global_atomic_add_f32 v45, v82, s[20:21] offset:512
	global_atomic_add_f32 v45, v83, s[20:21] offset:768
	s_add_u32 s20, s20, 0x6000
	s_addc_u32 s21, s21, 0
	global_atomic_add_f32 v45, v84, s[20:21] offset:0
	global_atomic_add_f32 v45, v85, s[20:21] offset:256
	global_atomic_add_f32 v45, v86, s[20:21] offset:512
	global_atomic_add_f32 v45, v87, s[20:21] offset:768
	s_add_u32 s20, s20, 0x6000
	s_addc_u32 s21, s21, 0
	global_atomic_add_f32 v45, v88, s[20:21] offset:0
	global_atomic_add_f32 v45, v89, s[20:21] offset:256
	global_atomic_add_f32 v45, v90, s[20:21] offset:512
	global_atomic_add_f32 v45, v91, s[20:21] offset:768
	s_add_u32 s20, s20, 0x6000
	s_addc_u32 s21, s21, 0
	global_atomic_add_f32 v45, v92, s[20:21] offset:0
	global_atomic_add_f32 v45, v93, s[20:21] offset:256
	global_atomic_add_f32 v45, v94, s[20:21] offset:512
	global_atomic_add_f32 v45, v95, s[20:21] offset:768
	s_add_u32 s20, s20, 0x6000
	s_addc_u32 s21, s21, 0
	global_atomic_add_f32 v45, v96, s[20:21] offset:0
	global_atomic_add_f32 v45, v97, s[20:21] offset:256
	global_atomic_add_f32 v45, v98, s[20:21] offset:512
	global_atomic_add_f32 v45, v99, s[20:21] offset:768
	s_add_u32 s20, s20, 0x6000
	s_addc_u32 s21, s21, 0
	global_atomic_add_f32 v45, v100, s[20:21] offset:0
	global_atomic_add_f32 v45, v101, s[20:21] offset:256
	global_atomic_add_f32 v45, v102, s[20:21] offset:512
	global_atomic_add_f32 v45, v103, s[20:21] offset:768
	s_add_u32 s20, s20, 0x6000
	s_addc_u32 s21, s21, 0
	global_atomic_add_f32 v45, v104, s[20:21] offset:0
	global_atomic_add_f32 v45, v105, s[20:21] offset:256
	global_atomic_add_f32 v45, v106, s[20:21] offset:512
	global_atomic_add_f32 v45, v107, s[20:21] offset:768
	s_add_u32 s20, s20, 0x6000
	s_addc_u32 s21, s21, 0
	global_atomic_add_f32 v45, v108, s[20:21] offset:0
	global_atomic_add_f32 v45, v109, s[20:21] offset:256
	global_atomic_add_f32 v45, v110, s[20:21] offset:512
	global_atomic_add_f32 v45, v111, s[20:21] offset:768
	s_add_u32 s20, s20, 0x6000
	s_addc_u32 s21, s21, 0
	global_atomic_add_f32 v45, v112, s[20:21] offset:0
	global_atomic_add_f32 v45, v113, s[20:21] offset:256
	global_atomic_add_f32 v45, v114, s[20:21] offset:512
	global_atomic_add_f32 v45, v115, s[20:21] offset:768
	s_mov_b32 s0, 2
